# v38 plus grid barrier pollers watch the cross-XCD arrival counter directly (skips the release-word round trip)
# baseline (speedup 1.0000x reference)
; __device__ __forceinline__ unsigned xb_ld(unsigned* p)              { return __hip_atomic_load(p, __ATOMIC_RELAXED, __HIP_MEMORY_SCOPE_AGENT); }
; __device__ __forceinline__ unsigned xb_add(unsigned* p, unsigned v) { return __hip_atomic_fetch_add(p, v, __ATOMIC_RELAXED, __HIP_MEMORY_SCOPE_AGENT); }
; #define XB_SPIN(cond, bar) do { unsigned _sp = 0; while (cond) { __builtin_amdgcn_s_sleep(1); \
;     if ((++_sp & 255u) == 0u) { if (xb_ld(&(bar)[XB_TMO])) break; if (_sp > XB_SPIN_CAP) { atomicAdd(&(bar)[XB_TMO], 1u); break; } } } } while (0)
; __device__ __forceinline__ void xcd_barrier(const XcdBarrier& b) {
;     ...
;         const unsigned old = xb_add(&bar[XB_XSUB(b.x)], 1u);
;         const unsigned gen = old / nloc;
;         if (old + 1u == (gen + 1u) * nloc) {
;             __builtin_amdgcn_fence(__ATOMIC_RELEASE, "agent");
;             asm volatile("s_waitcnt vmcnt(0)" ::: "memory");
;             const unsigned og = xb_add(&bar[XB_TOP], 1u);
;             const unsigned tg = og / nx;
;             if (og + 1u == (tg + 1u) * nx) xb_add(&bar[XB_TOPGEN], 1u);
;             else XB_SPIN(xb_ld(&bar[XB_TOPGEN]) == tg, bar);
;             __builtin_amdgcn_fence(__ATOMIC_ACQUIRE, "agent");
;             xb_add(&bar[XB_XGEN(b.x)], 1u);
;             asm volatile("s_waitcnt vmcnt(0)" ::: "memory");
;         } else {
;             XB_SPIN(xb_ld(&bar[XB_XGEN(b.x)]) == gen, bar);
.LBB0_201:
	s_or_b64 exec, exec, s[14:15]
	v_cvt_f32_u32_e32 v4, v2
	s_waitcnt vmcnt(0)
	v_readfirstlane_b32 s1, v3
	v_sub_u32_e32 v3, 0, v2
	v_rcp_iflag_f32_e32 v4, v4
	v_add_u32_e32 v5, s1, v1
	v_mul_f32_e32 v4, 0x4f7ffffe, v4
	v_cvt_u32_f32_e32 v4, v4
	v_mul_lo_u32 v1, v3, v4
	v_mul_hi_u32 v1, v4, v1
	v_add_u32_e32 v1, v4, v1
	v_mul_hi_u32 v1, v5, v1
	v_mul_lo_u32 v3, v1, v2
	v_sub_u32_e32 v3, v5, v3
	v_add_u32_e32 v4, 1, v1
	v_cmp_ge_u32_e32 vcc, v3, v2
	s_nop 1
	v_cndmask_b32_e32 v1, v1, v4, vcc
	v_sub_u32_e32 v4, v3, v2
	v_cndmask_b32_e32 v3, v3, v4, vcc
	v_add_u32_e32 v4, 1, v1
	v_cmp_ge_u32_e32 vcc, v3, v2
	v_add_u32_e32 v3, 1, v5
	s_nop 0
	v_cndmask_b32_e32 v1, v1, v4, vcc
	v_mul_lo_u32 v4, v2, v1
	v_add_u32_e32 v2, v4, v2
	v_cmp_ne_u32_e32 vcc, v3, v2
	s_and_saveexec_b64 s[6:7], vcc
	s_xor_b64 s[12:13], exec, s[6:7]
	s_cbranch_execz .LBB0_215
	s_waitcnt lgkmcnt(0)
	v_mov_b32_e32 v0, 0x20044
	ds_read_b32 v2, v0
	v_mov_b32_e32 v0, 0x7000
	global_load_dword v0, v0, s[8:9] offset:1024 sc1
	s_add_u32 s18, s8, 0x7400
	s_addc_u32 s19, s9, 0
	s_waitcnt lgkmcnt(0)
	v_mad_u32_u24 v1, v1, v2, v2
	s_waitcnt vmcnt(0)
	v_cmp_lt_u32_e32 vcc, v0, v1
	s_and_saveexec_b64 s[14:15], vcc
	s_cbranch_execz .LBB0_214
	s_add_u32 s16, s8, 0x4200
	s_addc_u32 s17, s9, 0
	s_mov_b32 s1, 1
	s_mov_b64 s[22:23], 0
	v_mov_b32_e32 v0, 0
	s_branch .LBB0_205

; __device__ __forceinline__ unsigned xb_ld(unsigned* p)              { return __hip_atomic_load(p, __ATOMIC_RELAXED, __HIP_MEMORY_SCOPE_AGENT); }
; #define XB_SPIN(cond, bar) do { unsigned _sp = 0; while (cond) { __builtin_amdgcn_s_sleep(1); \
;     if ((++_sp & 255u) == 0u) { if (xb_ld(&(bar)[XB_TMO])) break; if (_sp > XB_SPIN_CAP) { atomicAdd(&(bar)[XB_TMO], 1u); break; } } } } while (0)
; __device__ __forceinline__ void xcd_barrier(const XcdBarrier& b) {
;     ...
;             XB_SPIN(xb_ld(&bar[XB_XGEN(b.x)]) == gen, bar);
.LBB0_209:
	global_load_dword v2, v0, s[18:19] sc1
	s_add_i32 s1, s1, 1
	s_mov_b64 s[34:35], -1
	s_waitcnt vmcnt(0)
	v_cmp_ge_u32_e32 vcc, v2, v1
	s_orn2_b64 s[26:27], vcc, exec
	s_branch .LBB0_204

; __device__ __forceinline__ unsigned xb_ld(unsigned* p)              { return __hip_atomic_load(p, __ATOMIC_RELAXED, __HIP_MEMORY_SCOPE_AGENT); }
; __device__ __forceinline__ unsigned xb_add(unsigned* p, unsigned v) { return __hip_atomic_fetch_add(p, v, __ATOMIC_RELAXED, __HIP_MEMORY_SCOPE_AGENT); }
; #define XB_SPIN(cond, bar) do { unsigned _sp = 0; while (cond) { __builtin_amdgcn_s_sleep(1); \
;     if ((++_sp & 255u) == 0u) { if (xb_ld(&(bar)[XB_TMO])) break; if (_sp > XB_SPIN_CAP) { atomicAdd(&(bar)[XB_TMO], 1u); break; } } } } while (0)
; __device__ __forceinline__ void xcd_barrier(const XcdBarrier& b) {
;     ...
;         if (old + 1u == (gen + 1u) * nloc) {
;             __builtin_amdgcn_fence(__ATOMIC_RELEASE, "agent");
;             asm volatile("s_waitcnt vmcnt(0)" ::: "memory");
;             const unsigned og = xb_add(&bar[XB_TOP], 1u);
;             const unsigned tg = og / nx;
;             if (og + 1u == (tg + 1u) * nx) xb_add(&bar[XB_TOPGEN], 1u);
;             else XB_SPIN(xb_ld(&bar[XB_TOPGEN]) == tg, bar);
.LBB0_218:
	s_or_b64 exec, exec, s[14:15]
	v_cvt_f32_u32_e32 v3, v0
	s_waitcnt vmcnt(0)
	v_readfirstlane_b32 s1, v2
	s_add_u32 s14, s8, 0x7500
	s_addc_u32 s15, s9, 0
	v_rcp_iflag_f32_e32 v3, v3
	v_add_u32_e32 v1, s1, v1
	v_add_u32_e32 v4, 1, v1
	s_mov_b64 s[16:17], -1
	v_mul_f32_e32 v2, 0x4f7ffffe, v3
	v_cvt_u32_f32_e32 v2, v2
	v_sub_u32_e32 v3, 0, v0
	v_mul_lo_u32 v3, v3, v2
	v_mul_hi_u32 v3, v2, v3
	v_add_u32_e32 v2, v2, v3
	v_mul_hi_u32 v2, v1, v2
	v_mul_lo_u32 v3, v2, v0
	v_sub_u32_e32 v1, v1, v3
	v_add_u32_e32 v5, 1, v2
	v_cmp_ge_u32_e32 vcc, v1, v0
	v_sub_u32_e32 v3, v1, v0
	s_nop 0
	v_cndmask_b32_e32 v2, v2, v5, vcc
	v_cndmask_b32_e32 v1, v1, v3, vcc
	v_add_u32_e32 v3, 1, v2
	v_cmp_ge_u32_e32 vcc, v1, v0
	s_nop 1
	v_cndmask_b32_e32 v2, v2, v3, vcc
	v_mul_lo_u32 v1, v0, v2
	v_add_u32_e32 v0, v1, v0
	v_cmp_ne_u32_e32 vcc, v4, v0
	v_mov_b32_e32 v2, v0
	v_mov_b64_e32 v[0:1], s[14:15]
	s_and_saveexec_b64 s[12:13], vcc
	s_cbranch_execz .LBB0_230
	v_mov_b32_e32 v0, 0
	global_load_dword v1, v0, s[14:15] offset:-256 sc1
	s_mov_b64 s[22:23], 0
	s_waitcnt vmcnt(0)
	v_cmp_lt_u32_e32 vcc, v1, v2
	s_and_saveexec_b64 s[18:19], vcc
	s_cbranch_execz .LBB0_229
	s_add_u32 s16, s8, 0x4200
	s_addc_u32 s17, s9, 0
	s_mov_b32 s1, 1
	s_mov_b64 s[8:9], 0
	s_branch .LBB0_222

; __device__ __forceinline__ unsigned xb_ld(unsigned* p)              { return __hip_atomic_load(p, __ATOMIC_RELAXED, __HIP_MEMORY_SCOPE_AGENT); }
; #define XB_SPIN(cond, bar) do { unsigned _sp = 0; while (cond) { __builtin_amdgcn_s_sleep(1); \
;     if ((++_sp & 255u) == 0u) { if (xb_ld(&(bar)[XB_TMO])) break; if (_sp > XB_SPIN_CAP) { atomicAdd(&(bar)[XB_TMO], 1u); break; } } } } while (0)
; __device__ __forceinline__ void xcd_barrier(const XcdBarrier& b) {
;     ...
;             else XB_SPIN(xb_ld(&bar[XB_TOPGEN]) == tg, bar);
.LBB0_226:
	global_load_dword v1, v0, s[14:15] offset:-256 sc1
	s_add_i32 s1, s1, 1
	s_mov_b64 s[24:25], -1
	s_waitcnt vmcnt(0)
	v_cmp_ge_u32_e32 vcc, v1, v2
	s_orn2_b64 s[34:35], vcc, exec
	s_branch .LBB0_221

; __device__ __forceinline__ unsigned xb_ld(unsigned* p)              { return __hip_atomic_load(p, __ATOMIC_RELAXED, __HIP_MEMORY_SCOPE_AGENT); }
; __device__ __forceinline__ unsigned xb_add(unsigned* p, unsigned v) { return __hip_atomic_fetch_add(p, v, __ATOMIC_RELAXED, __HIP_MEMORY_SCOPE_AGENT); }
; #define XB_SPIN(cond, bar) do { unsigned _sp = 0; while (cond) { __builtin_amdgcn_s_sleep(1); \
;     if ((++_sp & 255u) == 0u) { if (xb_ld(&(bar)[XB_TMO])) break; if (_sp > XB_SPIN_CAP) { atomicAdd(&(bar)[XB_TMO], 1u); break; } } } } while (0)
; __device__ __forceinline__ void xcd_barrier(const XcdBarrier& b) {
;     ...
;         const unsigned old = xb_add(&bar[XB_XSUB(b.x)], 1u);
;         const unsigned gen = old / nloc;
;         if (old + 1u == (gen + 1u) * nloc) {
;             __builtin_amdgcn_fence(__ATOMIC_RELEASE, "agent");
;             asm volatile("s_waitcnt vmcnt(0)" ::: "memory");
;             const unsigned og = xb_add(&bar[XB_TOP], 1u);
;             const unsigned tg = og / nx;
;             if (og + 1u == (tg + 1u) * nx) xb_add(&bar[XB_TOPGEN], 1u);
;             else XB_SPIN(xb_ld(&bar[XB_TOPGEN]) == tg, bar);
;             __builtin_amdgcn_fence(__ATOMIC_ACQUIRE, "agent");
;             xb_add(&bar[XB_XGEN(b.x)], 1u);
;             asm volatile("s_waitcnt vmcnt(0)" ::: "memory");
;         } else {
;             XB_SPIN(xb_ld(&bar[XB_XGEN(b.x)]) == gen, bar);
.LBB0_265:
	s_or_b64 exec, exec, s[18:19]
	v_cvt_f32_u32_e32 v4, v2
	s_waitcnt vmcnt(0)
	v_readfirstlane_b32 s1, v3
	v_sub_u32_e32 v3, 0, v2
	v_rcp_iflag_f32_e32 v4, v4
	v_add_u32_e32 v5, s1, v1
	v_mul_f32_e32 v4, 0x4f7ffffe, v4
	v_cvt_u32_f32_e32 v4, v4
	v_mul_lo_u32 v1, v3, v4
	v_mul_hi_u32 v1, v4, v1
	v_add_u32_e32 v1, v4, v1
	v_mul_hi_u32 v1, v5, v1
	v_mul_lo_u32 v3, v1, v2
	v_sub_u32_e32 v3, v5, v3
	v_add_u32_e32 v4, 1, v1
	v_cmp_ge_u32_e32 vcc, v3, v2
	s_nop 1
	v_cndmask_b32_e32 v1, v1, v4, vcc
	v_sub_u32_e32 v4, v3, v2
	v_cndmask_b32_e32 v3, v3, v4, vcc
	v_add_u32_e32 v4, 1, v1
	v_cmp_ge_u32_e32 vcc, v3, v2
	v_add_u32_e32 v3, 1, v5
	s_nop 0
	v_cndmask_b32_e32 v1, v1, v4, vcc
	v_mul_lo_u32 v4, v2, v1
	v_add_u32_e32 v2, v4, v2
	v_cmp_ne_u32_e32 vcc, v3, v2
	s_and_saveexec_b64 s[14:15], vcc
	s_xor_b64 s[14:15], exec, s[14:15]
	s_cbranch_execz .LBB0_279
	s_waitcnt lgkmcnt(0)
	v_mov_b32_e32 v0, 0x20044
	ds_read_b32 v2, v0
	v_mov_b32_e32 v0, 0x7000
	global_load_dword v0, v0, s[10:11] offset:1024 sc1
	s_add_u32 s24, s10, 0x7400
	s_addc_u32 s25, s11, 0
	s_waitcnt lgkmcnt(0)
	v_mad_u32_u24 v1, v1, v2, v2
	s_waitcnt vmcnt(0)
	v_cmp_lt_u32_e32 vcc, v0, v1
	s_and_saveexec_b64 s[18:19], vcc
	s_cbranch_execz .LBB0_278
	s_add_u32 s22, s10, 0x4200
	s_addc_u32 s23, s11, 0
	s_mov_b32 s1, 1
	s_mov_b64 s[26:27], 0
	v_mov_b32_e32 v0, 0
	s_branch .LBB0_269

; __device__ __forceinline__ unsigned xb_ld(unsigned* p)              { return __hip_atomic_load(p, __ATOMIC_RELAXED, __HIP_MEMORY_SCOPE_AGENT); }
; #define XB_SPIN(cond, bar) do { unsigned _sp = 0; while (cond) { __builtin_amdgcn_s_sleep(1); \
;     if ((++_sp & 255u) == 0u) { if (xb_ld(&(bar)[XB_TMO])) break; if (_sp > XB_SPIN_CAP) { atomicAdd(&(bar)[XB_TMO], 1u); break; } } } } while (0)
; __device__ __forceinline__ void xcd_barrier(const XcdBarrier& b) {
;     ...
;             XB_SPIN(xb_ld(&bar[XB_XGEN(b.x)]) == gen, bar);
.LBB0_273:
	global_load_dword v2, v0, s[24:25] sc1
	s_add_i32 s1, s1, 1
	s_mov_b64 s[38:39], -1
	s_waitcnt vmcnt(0)
	v_cmp_ge_u32_e32 vcc, v2, v1
	s_orn2_b64 s[36:37], vcc, exec
	s_branch .LBB0_268

; __device__ __forceinline__ unsigned xb_ld(unsigned* p)              { return __hip_atomic_load(p, __ATOMIC_RELAXED, __HIP_MEMORY_SCOPE_AGENT); }
; __device__ __forceinline__ unsigned xb_add(unsigned* p, unsigned v) { return __hip_atomic_fetch_add(p, v, __ATOMIC_RELAXED, __HIP_MEMORY_SCOPE_AGENT); }
; #define XB_SPIN(cond, bar) do { unsigned _sp = 0; while (cond) { __builtin_amdgcn_s_sleep(1); \
;     if ((++_sp & 255u) == 0u) { if (xb_ld(&(bar)[XB_TMO])) break; if (_sp > XB_SPIN_CAP) { atomicAdd(&(bar)[XB_TMO], 1u); break; } } } } while (0)
; __device__ __forceinline__ void xcd_barrier(const XcdBarrier& b) {
;     ...
;         if (old + 1u == (gen + 1u) * nloc) {
;             __builtin_amdgcn_fence(__ATOMIC_RELEASE, "agent");
;             asm volatile("s_waitcnt vmcnt(0)" ::: "memory");
;             const unsigned og = xb_add(&bar[XB_TOP], 1u);
;             const unsigned tg = og / nx;
;             if (og + 1u == (tg + 1u) * nx) xb_add(&bar[XB_TOPGEN], 1u);
;             else XB_SPIN(xb_ld(&bar[XB_TOPGEN]) == tg, bar);
.LBB0_282:
	s_or_b64 exec, exec, s[18:19]
	v_cvt_f32_u32_e32 v3, v0
	s_waitcnt vmcnt(0)
	v_readfirstlane_b32 s1, v2
	s_add_u32 s18, s10, 0x7500
	s_addc_u32 s19, s11, 0
	v_rcp_iflag_f32_e32 v3, v3
	v_add_u32_e32 v1, s1, v1
	v_add_u32_e32 v4, 1, v1
	s_mov_b64 s[22:23], -1
	v_mul_f32_e32 v2, 0x4f7ffffe, v3
	v_cvt_u32_f32_e32 v2, v2
	v_sub_u32_e32 v3, 0, v0
	v_mul_lo_u32 v3, v3, v2
	v_mul_hi_u32 v3, v2, v3
	v_add_u32_e32 v2, v2, v3
	v_mul_hi_u32 v2, v1, v2
	v_mul_lo_u32 v3, v2, v0
	v_sub_u32_e32 v1, v1, v3
	v_add_u32_e32 v5, 1, v2
	v_cmp_ge_u32_e32 vcc, v1, v0
	v_sub_u32_e32 v3, v1, v0
	s_nop 0
	v_cndmask_b32_e32 v2, v2, v5, vcc
	v_cndmask_b32_e32 v1, v1, v3, vcc
	v_add_u32_e32 v3, 1, v2
	v_cmp_ge_u32_e32 vcc, v1, v0
	s_nop 1
	v_cndmask_b32_e32 v2, v2, v3, vcc
	v_mul_lo_u32 v1, v0, v2
	v_add_u32_e32 v0, v1, v0
	v_cmp_ne_u32_e32 vcc, v4, v0
	v_mov_b32_e32 v2, v0
	v_mov_b64_e32 v[0:1], s[18:19]
	s_and_saveexec_b64 s[14:15], vcc
	s_cbranch_execz .LBB0_294
	v_mov_b32_e32 v0, 0
	global_load_dword v1, v0, s[18:19] offset:-256 sc1
	s_mov_b64 s[26:27], 0
	s_waitcnt vmcnt(0)
	v_cmp_lt_u32_e32 vcc, v1, v2
	s_and_saveexec_b64 s[24:25], vcc
	s_cbranch_execz .LBB0_293
	s_add_u32 s22, s10, 0x4200
	s_addc_u32 s23, s11, 0
	s_mov_b32 s1, 1
	s_mov_b64 s[10:11], 0
	s_branch .LBB0_286

; __device__ __forceinline__ unsigned xb_ld(unsigned* p)              { return __hip_atomic_load(p, __ATOMIC_RELAXED, __HIP_MEMORY_SCOPE_AGENT); }
; #define XB_SPIN(cond, bar) do { unsigned _sp = 0; while (cond) { __builtin_amdgcn_s_sleep(1); \
;     if ((++_sp & 255u) == 0u) { if (xb_ld(&(bar)[XB_TMO])) break; if (_sp > XB_SPIN_CAP) { atomicAdd(&(bar)[XB_TMO], 1u); break; } } } } while (0)
; __device__ __forceinline__ void xcd_barrier(const XcdBarrier& b) {
;     ...
;             else XB_SPIN(xb_ld(&bar[XB_TOPGEN]) == tg, bar);
.LBB0_290:
	global_load_dword v1, v0, s[18:19] offset:-256 sc1
	s_add_i32 s1, s1, 1
	s_mov_b64 s[34:35], -1
	s_waitcnt vmcnt(0)
	v_cmp_ge_u32_e32 vcc, v1, v2
	s_orn2_b64 s[38:39], vcc, exec
	s_branch .LBB0_285

; __device__ __forceinline__ unsigned xb_ld(unsigned* p)              { return __hip_atomic_load(p, __ATOMIC_RELAXED, __HIP_MEMORY_SCOPE_AGENT); }
; __device__ __forceinline__ unsigned xb_add(unsigned* p, unsigned v) { return __hip_atomic_fetch_add(p, v, __ATOMIC_RELAXED, __HIP_MEMORY_SCOPE_AGENT); }
; #define XB_SPIN(cond, bar) do { unsigned _sp = 0; while (cond) { __builtin_amdgcn_s_sleep(1); \
;     if ((++_sp & 255u) == 0u) { if (xb_ld(&(bar)[XB_TMO])) break; if (_sp > XB_SPIN_CAP) { atomicAdd(&(bar)[XB_TMO], 1u); break; } } } } while (0)
; __device__ __forceinline__ void xcd_barrier(const XcdBarrier& b) {
;     ...
;         const unsigned old = xb_add(&bar[XB_XSUB(b.x)], 1u);
;         const unsigned gen = old / nloc;
;         if (old + 1u == (gen + 1u) * nloc) {
;             __builtin_amdgcn_fence(__ATOMIC_RELEASE, "agent");
;             asm volatile("s_waitcnt vmcnt(0)" ::: "memory");
;             const unsigned og = xb_add(&bar[XB_TOP], 1u);
;             const unsigned tg = og / nx;
;             if (og + 1u == (tg + 1u) * nx) xb_add(&bar[XB_TOPGEN], 1u);
;             else XB_SPIN(xb_ld(&bar[XB_TOPGEN]) == tg, bar);
;             __builtin_amdgcn_fence(__ATOMIC_ACQUIRE, "agent");
;             xb_add(&bar[XB_XGEN(b.x)], 1u);
;             asm volatile("s_waitcnt vmcnt(0)" ::: "memory");
;         } else {
;             XB_SPIN(xb_ld(&bar[XB_XGEN(b.x)]) == gen, bar);
.LBB0_477:
	s_or_b64 exec, exec, s[18:19]
	v_cvt_f32_u32_e32 v4, v2
	s_waitcnt vmcnt(0)
	v_readfirstlane_b32 s1, v3
	v_sub_u32_e32 v3, 0, v2
	v_rcp_iflag_f32_e32 v4, v4
	v_add_u32_e32 v5, s1, v1
	v_mul_f32_e32 v4, 0x4f7ffffe, v4
	v_cvt_u32_f32_e32 v4, v4
	v_mul_lo_u32 v1, v3, v4
	v_mul_hi_u32 v1, v4, v1
	v_add_u32_e32 v1, v4, v1
	v_mul_hi_u32 v1, v5, v1
	v_mul_lo_u32 v3, v1, v2
	v_sub_u32_e32 v3, v5, v3
	v_add_u32_e32 v4, 1, v1
	v_cmp_ge_u32_e32 vcc, v3, v2
	s_nop 1
	v_cndmask_b32_e32 v1, v1, v4, vcc
	v_sub_u32_e32 v4, v3, v2
	v_cndmask_b32_e32 v3, v3, v4, vcc
	v_add_u32_e32 v4, 1, v1
	v_cmp_ge_u32_e32 vcc, v3, v2
	v_add_u32_e32 v3, 1, v5
	s_nop 0
	v_cndmask_b32_e32 v1, v1, v4, vcc
	v_mul_lo_u32 v4, v2, v1
	v_add_u32_e32 v2, v4, v2
	v_cmp_ne_u32_e32 vcc, v3, v2
	s_and_saveexec_b64 s[4:5], vcc
	s_xor_b64 s[16:17], exec, s[4:5]
	s_cbranch_execz .LBB0_491
	s_waitcnt lgkmcnt(0)
	v_mov_b32_e32 v0, 0x20044
	ds_read_b32 v2, v0
	v_mov_b32_e32 v0, 0x7000
	global_load_dword v0, v0, s[12:13] offset:1024 sc1
	s_add_u32 s24, s12, 0x7400
	s_addc_u32 s25, s13, 0
	s_waitcnt lgkmcnt(0)
	v_mad_u32_u24 v1, v1, v2, v2
	s_waitcnt vmcnt(0)
	v_cmp_lt_u32_e32 vcc, v0, v1
	s_and_saveexec_b64 s[18:19], vcc
	s_cbranch_execz .LBB0_490
	s_add_u32 s22, s12, 0x4200
	s_addc_u32 s23, s13, 0
	s_mov_b32 s1, 1
	s_mov_b64 s[26:27], 0
	v_mov_b32_e32 v0, 0
	s_branch .LBB0_481

; __device__ __forceinline__ unsigned xb_ld(unsigned* p)              { return __hip_atomic_load(p, __ATOMIC_RELAXED, __HIP_MEMORY_SCOPE_AGENT); }
; __device__ __forceinline__ unsigned xb_add(unsigned* p, unsigned v) { return __hip_atomic_fetch_add(p, v, __ATOMIC_RELAXED, __HIP_MEMORY_SCOPE_AGENT); }
; #define XB_SPIN(cond, bar) do { unsigned _sp = 0; while (cond) { __builtin_amdgcn_s_sleep(1); \
;     if ((++_sp & 255u) == 0u) { if (xb_ld(&(bar)[XB_TMO])) break; if (_sp > XB_SPIN_CAP) { atomicAdd(&(bar)[XB_TMO], 1u); break; } } } } while (0)
; __device__ __forceinline__ void xcd_barrier(const XcdBarrier& b) {
;     ...
;         if (old + 1u == (gen + 1u) * nloc) {
;             __builtin_amdgcn_fence(__ATOMIC_RELEASE, "agent");
;             asm volatile("s_waitcnt vmcnt(0)" ::: "memory");
;             const unsigned og = xb_add(&bar[XB_TOP], 1u);
;             const unsigned tg = og / nx;
;             if (og + 1u == (tg + 1u) * nx) xb_add(&bar[XB_TOPGEN], 1u);
;             else XB_SPIN(xb_ld(&bar[XB_TOPGEN]) == tg, bar);
.LBB0_494:
	s_or_b64 exec, exec, s[18:19]
	v_cvt_f32_u32_e32 v3, v0
	s_waitcnt vmcnt(0)
	v_readfirstlane_b32 s1, v2
	s_add_u32 s18, s12, 0x7500
	s_addc_u32 s19, s13, 0
	v_rcp_iflag_f32_e32 v3, v3
	v_add_u32_e32 v1, s1, v1
	v_add_u32_e32 v4, 1, v1
	s_mov_b64 s[22:23], -1
	v_mul_f32_e32 v2, 0x4f7ffffe, v3
	v_cvt_u32_f32_e32 v2, v2
	v_sub_u32_e32 v3, 0, v0
	v_mul_lo_u32 v3, v3, v2
	v_mul_hi_u32 v3, v2, v3
	v_add_u32_e32 v2, v2, v3
	v_mul_hi_u32 v2, v1, v2
	v_mul_lo_u32 v3, v2, v0
	v_sub_u32_e32 v1, v1, v3
	v_add_u32_e32 v5, 1, v2
	v_cmp_ge_u32_e32 vcc, v1, v0
	v_sub_u32_e32 v3, v1, v0
	s_nop 0
	v_cndmask_b32_e32 v2, v2, v5, vcc
	v_cndmask_b32_e32 v1, v1, v3, vcc
	v_add_u32_e32 v3, 1, v2
	v_cmp_ge_u32_e32 vcc, v1, v0
	s_nop 1
	v_cndmask_b32_e32 v2, v2, v3, vcc
	v_mul_lo_u32 v1, v0, v2
	v_add_u32_e32 v0, v1, v0
	v_cmp_ne_u32_e32 vcc, v4, v0
	v_mov_b32_e32 v2, v0
	v_mov_b64_e32 v[0:1], s[18:19]
	s_and_saveexec_b64 s[16:17], vcc
	s_cbranch_execz .LBB0_506
	v_mov_b32_e32 v0, 0
	global_load_dword v1, v0, s[18:19] offset:-256 sc1
	s_mov_b64 s[26:27], 0
	s_waitcnt vmcnt(0)
	v_cmp_lt_u32_e32 vcc, v1, v2
	s_and_saveexec_b64 s[24:25], vcc
	s_cbranch_execz .LBB0_505
	s_add_u32 s22, s12, 0x4200
	s_addc_u32 s23, s13, 0
	s_mov_b32 s1, 1
	s_mov_b64 s[12:13], 0
	s_branch .LBB0_498

; __device__ __forceinline__ unsigned xb_ld(unsigned* p)              { return __hip_atomic_load(p, __ATOMIC_RELAXED, __HIP_MEMORY_SCOPE_AGENT); }
; __device__ __forceinline__ unsigned xb_add(unsigned* p, unsigned v) { return __hip_atomic_fetch_add(p, v, __ATOMIC_RELAXED, __HIP_MEMORY_SCOPE_AGENT); }
; #define XB_SPIN(cond, bar) do { unsigned _sp = 0; while (cond) { __builtin_amdgcn_s_sleep(1); \
;     if ((++_sp & 255u) == 0u) { if (xb_ld(&(bar)[XB_TMO])) break; if (_sp > XB_SPIN_CAP) { atomicAdd(&(bar)[XB_TMO], 1u); break; } } } } while (0)
; __device__ __forceinline__ void xcd_barrier(const XcdBarrier& b) {
;     ...
;         const unsigned old = xb_add(&bar[XB_XSUB(b.x)], 1u);
;         const unsigned gen = old / nloc;
;         if (old + 1u == (gen + 1u) * nloc) {
;             __builtin_amdgcn_fence(__ATOMIC_RELEASE, "agent");
;             asm volatile("s_waitcnt vmcnt(0)" ::: "memory");
;             const unsigned og = xb_add(&bar[XB_TOP], 1u);
;             const unsigned tg = og / nx;
;             if (og + 1u == (tg + 1u) * nx) xb_add(&bar[XB_TOPGEN], 1u);
;             else XB_SPIN(xb_ld(&bar[XB_TOPGEN]) == tg, bar);
;             __builtin_amdgcn_fence(__ATOMIC_ACQUIRE, "agent");
;             xb_add(&bar[XB_XGEN(b.x)], 1u);
;             asm volatile("s_waitcnt vmcnt(0)" ::: "memory");
;         } else {
;             XB_SPIN(xb_ld(&bar[XB_XGEN(b.x)]) == gen, bar);
.LBB0_753:
	s_or_b64 exec, exec, s[20:21]
	v_cvt_f32_u32_e32 v4, v2
	s_waitcnt vmcnt(0)
	v_readfirstlane_b32 s1, v3
	v_sub_u32_e32 v3, 0, v2
	v_rcp_iflag_f32_e32 v4, v4
	v_add_u32_e32 v5, s1, v1
	v_mul_f32_e32 v4, 0x4f7ffffe, v4
	v_cvt_u32_f32_e32 v4, v4
	v_mul_lo_u32 v1, v3, v4
	v_mul_hi_u32 v1, v4, v1
	v_add_u32_e32 v1, v4, v1
	v_mul_hi_u32 v1, v5, v1
	v_mul_lo_u32 v3, v1, v2
	v_sub_u32_e32 v3, v5, v3
	v_add_u32_e32 v4, 1, v1
	v_cmp_ge_u32_e32 vcc, v3, v2
	s_nop 1
	v_cndmask_b32_e32 v1, v1, v4, vcc
	v_sub_u32_e32 v4, v3, v2
	v_cndmask_b32_e32 v3, v3, v4, vcc
	v_add_u32_e32 v4, 1, v1
	v_cmp_ge_u32_e32 vcc, v3, v2
	v_add_u32_e32 v3, 1, v5
	s_nop 0
	v_cndmask_b32_e32 v1, v1, v4, vcc
	v_mul_lo_u32 v4, v2, v1
	v_add_u32_e32 v2, v4, v2
	v_cmp_ne_u32_e32 vcc, v3, v2
	s_and_saveexec_b64 s[4:5], vcc
	s_xor_b64 s[18:19], exec, s[4:5]
	s_cbranch_execz .LBB0_767
	s_waitcnt lgkmcnt(0)
	v_mov_b32_e32 v0, 0x20044
	ds_read_b32 v2, v0
	v_mov_b32_e32 v0, 0x7000
	global_load_dword v0, v0, s[12:13] offset:1024 sc1
	s_add_u32 s24, s12, 0x7400
	s_addc_u32 s25, s13, 0
	s_waitcnt lgkmcnt(0)
	v_mad_u32_u24 v1, v1, v2, v2
	s_waitcnt vmcnt(0)
	v_cmp_lt_u32_e32 vcc, v0, v1
	s_and_saveexec_b64 s[20:21], vcc
	s_cbranch_execz .LBB0_766
	s_add_u32 s22, s12, 0x4200
	s_addc_u32 s23, s13, 0
	s_mov_b32 s1, 1
	s_mov_b64 s[26:27], 0
	v_mov_b32_e32 v0, 0
	s_branch .LBB0_757

; __device__ __forceinline__ unsigned xb_ld(unsigned* p)              { return __hip_atomic_load(p, __ATOMIC_RELAXED, __HIP_MEMORY_SCOPE_AGENT); }
; __device__ __forceinline__ unsigned xb_add(unsigned* p, unsigned v) { return __hip_atomic_fetch_add(p, v, __ATOMIC_RELAXED, __HIP_MEMORY_SCOPE_AGENT); }
; #define XB_SPIN(cond, bar) do { unsigned _sp = 0; while (cond) { __builtin_amdgcn_s_sleep(1); \
;     if ((++_sp & 255u) == 0u) { if (xb_ld(&(bar)[XB_TMO])) break; if (_sp > XB_SPIN_CAP) { atomicAdd(&(bar)[XB_TMO], 1u); break; } } } } while (0)
; __device__ __forceinline__ void xcd_barrier(const XcdBarrier& b) {
;     ...
;         if (old + 1u == (gen + 1u) * nloc) {
;             __builtin_amdgcn_fence(__ATOMIC_RELEASE, "agent");
;             asm volatile("s_waitcnt vmcnt(0)" ::: "memory");
;             const unsigned og = xb_add(&bar[XB_TOP], 1u);
;             const unsigned tg = og / nx;
;             if (og + 1u == (tg + 1u) * nx) xb_add(&bar[XB_TOPGEN], 1u);
;             else XB_SPIN(xb_ld(&bar[XB_TOPGEN]) == tg, bar);
.LBB0_770:
	s_or_b64 exec, exec, s[20:21]
	v_cvt_f32_u32_e32 v3, v0
	s_waitcnt vmcnt(0)
	v_readfirstlane_b32 s1, v2
	s_add_u32 s20, s12, 0x7500
	s_addc_u32 s21, s13, 0
	v_rcp_iflag_f32_e32 v3, v3
	v_add_u32_e32 v1, s1, v1
	v_add_u32_e32 v4, 1, v1
	s_mov_b64 s[22:23], -1
	v_mul_f32_e32 v2, 0x4f7ffffe, v3
	v_cvt_u32_f32_e32 v2, v2
	v_sub_u32_e32 v3, 0, v0
	v_mul_lo_u32 v3, v3, v2
	v_mul_hi_u32 v3, v2, v3
	v_add_u32_e32 v2, v2, v3
	v_mul_hi_u32 v2, v1, v2
	v_mul_lo_u32 v3, v2, v0
	v_sub_u32_e32 v1, v1, v3
	v_add_u32_e32 v5, 1, v2
	v_cmp_ge_u32_e32 vcc, v1, v0
	v_sub_u32_e32 v3, v1, v0
	s_nop 0
	v_cndmask_b32_e32 v2, v2, v5, vcc
	v_cndmask_b32_e32 v1, v1, v3, vcc
	v_add_u32_e32 v3, 1, v2
	v_cmp_ge_u32_e32 vcc, v1, v0
	s_nop 1
	v_cndmask_b32_e32 v2, v2, v3, vcc
	v_mul_lo_u32 v1, v0, v2
	v_add_u32_e32 v0, v1, v0
	v_cmp_ne_u32_e32 vcc, v4, v0
	v_mov_b32_e32 v2, v0
	v_mov_b64_e32 v[0:1], s[20:21]
	s_and_saveexec_b64 s[18:19], vcc
	s_cbranch_execz .LBB0_782
	v_mov_b32_e32 v0, 0
	global_load_dword v1, v0, s[20:21] offset:-256 sc1
	s_mov_b64 s[26:27], 0
	s_waitcnt vmcnt(0)
	v_cmp_lt_u32_e32 vcc, v1, v2
	s_and_saveexec_b64 s[24:25], vcc
	s_cbranch_execz .LBB0_781
	s_add_u32 s22, s12, 0x4200
	s_addc_u32 s23, s13, 0
	s_mov_b32 s1, 1
	s_mov_b64 s[12:13], 0
	s_branch .LBB0_774

; __device__ __forceinline__ unsigned xb_ld(unsigned* p)              { return __hip_atomic_load(p, __ATOMIC_RELAXED, __HIP_MEMORY_SCOPE_AGENT); }
; #define XB_SPIN(cond, bar) do { unsigned _sp = 0; while (cond) { __builtin_amdgcn_s_sleep(1); \
;     if ((++_sp & 255u) == 0u) { if (xb_ld(&(bar)[XB_TMO])) break; if (_sp > XB_SPIN_CAP) { atomicAdd(&(bar)[XB_TMO], 1u); break; } } } } while (0)
; __device__ __forceinline__ void xcd_barrier(const XcdBarrier& b) {
;     ...
;             else XB_SPIN(xb_ld(&bar[XB_TOPGEN]) == tg, bar);
.LBB0_778:
	global_load_dword v1, v0, s[20:21] offset:-256 sc1
	s_add_i32 s1, s1, 1
	s_mov_b64 s[34:35], -1
	s_waitcnt vmcnt(0)
	v_cmp_ge_u32_e32 vcc, v1, v2
	s_orn2_b64 s[38:39], vcc, exec
	s_branch .LBB0_773

; __device__ __forceinline__ unsigned xb_ld(unsigned* p)              { return __hip_atomic_load(p, __ATOMIC_RELAXED, __HIP_MEMORY_SCOPE_AGENT); }
; __device__ __forceinline__ unsigned xb_add(unsigned* p, unsigned v) { return __hip_atomic_fetch_add(p, v, __ATOMIC_RELAXED, __HIP_MEMORY_SCOPE_AGENT); }
; #define XB_SPIN(cond, bar) do { unsigned _sp = 0; while (cond) { __builtin_amdgcn_s_sleep(1); \
;     if ((++_sp & 255u) == 0u) { if (xb_ld(&(bar)[XB_TMO])) break; if (_sp > XB_SPIN_CAP) { atomicAdd(&(bar)[XB_TMO], 1u); break; } } } } while (0)
; __device__ __forceinline__ void xcd_barrier(const XcdBarrier& b) {
;     ...
;         const unsigned old = xb_add(&bar[XB_XSUB(b.x)], 1u);
;         const unsigned gen = old / nloc;
;         if (old + 1u == (gen + 1u) * nloc) {
;             __builtin_amdgcn_fence(__ATOMIC_RELEASE, "agent");
;             asm volatile("s_waitcnt vmcnt(0)" ::: "memory");
;             const unsigned og = xb_add(&bar[XB_TOP], 1u);
;             const unsigned tg = og / nx;
;             if (og + 1u == (tg + 1u) * nx) xb_add(&bar[XB_TOPGEN], 1u);
;             else XB_SPIN(xb_ld(&bar[XB_TOPGEN]) == tg, bar);
;             __builtin_amdgcn_fence(__ATOMIC_ACQUIRE, "agent");
;             xb_add(&bar[XB_XGEN(b.x)], 1u);
;             asm volatile("s_waitcnt vmcnt(0)" ::: "memory");
;         } else {
;             XB_SPIN(xb_ld(&bar[XB_XGEN(b.x)]) == gen, bar);
.LBB0_859:
	s_or_b64 exec, exec, s[22:23]
	v_cvt_f32_u32_e32 v4, v2
	s_waitcnt vmcnt(0)
	v_readfirstlane_b32 s0, v3
	v_sub_u32_e32 v3, 0, v2
	v_rcp_iflag_f32_e32 v4, v4
	v_add_u32_e32 v5, s0, v1
	v_mul_f32_e32 v4, 0x4f7ffffe, v4
	v_cvt_u32_f32_e32 v4, v4
	v_mul_lo_u32 v1, v3, v4
	v_mul_hi_u32 v1, v4, v1
	v_add_u32_e32 v1, v4, v1
	v_mul_hi_u32 v1, v5, v1
	v_mul_lo_u32 v3, v1, v2
	v_sub_u32_e32 v3, v5, v3
	v_add_u32_e32 v4, 1, v1
	v_cmp_ge_u32_e32 vcc, v3, v2
	s_nop 1
	v_cndmask_b32_e32 v1, v1, v4, vcc
	v_sub_u32_e32 v4, v3, v2
	v_cndmask_b32_e32 v3, v3, v4, vcc
	v_add_u32_e32 v4, 1, v1
	v_cmp_ge_u32_e32 vcc, v3, v2
	v_add_u32_e32 v3, 1, v5
	s_nop 0
	v_cndmask_b32_e32 v1, v1, v4, vcc
	v_mul_lo_u32 v4, v2, v1
	v_add_u32_e32 v2, v4, v2
	v_cmp_ne_u32_e32 vcc, v3, v2
	s_and_saveexec_b64 s[14:15], vcc
	s_xor_b64 s[20:21], exec, s[14:15]
	s_cbranch_execz .LBB0_873
	s_waitcnt lgkmcnt(0)
	v_mov_b32_e32 v0, 0x20044
	ds_read_b32 v2, v0
	v_mov_b32_e32 v0, 0x7000
	global_load_dword v0, v0, s[16:17] offset:1024 sc1
	s_add_u32 s26, s16, 0x7400
	s_addc_u32 s27, s17, 0
	s_waitcnt lgkmcnt(0)
	v_mad_u32_u24 v1, v1, v2, v2
	s_waitcnt vmcnt(0)
	v_cmp_lt_u32_e32 vcc, v0, v1
	s_and_saveexec_b64 s[22:23], vcc
	s_cbranch_execz .LBB0_872
	s_add_u32 s24, s16, 0x4200
	s_addc_u32 s25, s17, 0
	s_mov_b32 s0, 1
	s_mov_b64 s[44:45], 0
	v_mov_b32_e32 v0, 0
	s_branch .LBB0_863

; __device__ __forceinline__ unsigned xb_ld(unsigned* p)              { return __hip_atomic_load(p, __ATOMIC_RELAXED, __HIP_MEMORY_SCOPE_AGENT); }
; #define XB_SPIN(cond, bar) do { unsigned _sp = 0; while (cond) { __builtin_amdgcn_s_sleep(1); \
;     if ((++_sp & 255u) == 0u) { if (xb_ld(&(bar)[XB_TMO])) break; if (_sp > XB_SPIN_CAP) { atomicAdd(&(bar)[XB_TMO], 1u); break; } } } } while (0)
; __device__ __forceinline__ void xcd_barrier(const XcdBarrier& b) {
;     ...
;             XB_SPIN(xb_ld(&bar[XB_XGEN(b.x)]) == gen, bar);
.LBB0_867:
	global_load_dword v2, v0, s[26:27] sc1
	s_add_i32 s0, s0, 1
	s_mov_b64 s[50:51], -1
	s_waitcnt vmcnt(0)
	v_cmp_ge_u32_e32 vcc, v2, v1
	s_orn2_b64 s[48:49], vcc, exec
	s_branch .LBB0_862

; __device__ __forceinline__ unsigned xb_ld(unsigned* p)              { return __hip_atomic_load(p, __ATOMIC_RELAXED, __HIP_MEMORY_SCOPE_AGENT); }
; __device__ __forceinline__ unsigned xb_add(unsigned* p, unsigned v) { return __hip_atomic_fetch_add(p, v, __ATOMIC_RELAXED, __HIP_MEMORY_SCOPE_AGENT); }
; #define XB_SPIN(cond, bar) do { unsigned _sp = 0; while (cond) { __builtin_amdgcn_s_sleep(1); \
;     if ((++_sp & 255u) == 0u) { if (xb_ld(&(bar)[XB_TMO])) break; if (_sp > XB_SPIN_CAP) { atomicAdd(&(bar)[XB_TMO], 1u); break; } } } } while (0)
; __device__ __forceinline__ void xcd_barrier(const XcdBarrier& b) {
;     ...
;         if (old + 1u == (gen + 1u) * nloc) {
;             __builtin_amdgcn_fence(__ATOMIC_RELEASE, "agent");
;             asm volatile("s_waitcnt vmcnt(0)" ::: "memory");
;             const unsigned og = xb_add(&bar[XB_TOP], 1u);
;             const unsigned tg = og / nx;
;             if (og + 1u == (tg + 1u) * nx) xb_add(&bar[XB_TOPGEN], 1u);
;             else XB_SPIN(xb_ld(&bar[XB_TOPGEN]) == tg, bar);
.LBB0_876:
	s_or_b64 exec, exec, s[22:23]
	v_cvt_f32_u32_e32 v3, v0
	s_waitcnt vmcnt(0)
	v_readfirstlane_b32 s0, v2
	s_add_u32 s22, s16, 0x7500
	s_addc_u32 s23, s17, 0
	v_rcp_iflag_f32_e32 v3, v3
	v_add_u32_e32 v1, s0, v1
	v_add_u32_e32 v4, 1, v1
	s_mov_b64 s[24:25], -1
	v_mul_f32_e32 v2, 0x4f7ffffe, v3
	v_cvt_u32_f32_e32 v2, v2
	v_sub_u32_e32 v3, 0, v0
	v_mul_lo_u32 v3, v3, v2
	v_mul_hi_u32 v3, v2, v3
	v_add_u32_e32 v2, v2, v3
	v_mul_hi_u32 v2, v1, v2
	v_mul_lo_u32 v3, v2, v0
	v_sub_u32_e32 v1, v1, v3
	v_add_u32_e32 v5, 1, v2
	v_cmp_ge_u32_e32 vcc, v1, v0
	v_sub_u32_e32 v3, v1, v0
	s_nop 0
	v_cndmask_b32_e32 v2, v2, v5, vcc
	v_cndmask_b32_e32 v1, v1, v3, vcc
	v_add_u32_e32 v3, 1, v2
	v_cmp_ge_u32_e32 vcc, v1, v0
	s_nop 1
	v_cndmask_b32_e32 v2, v2, v3, vcc
	v_mul_lo_u32 v1, v0, v2
	v_add_u32_e32 v0, v1, v0
	v_cmp_ne_u32_e32 vcc, v4, v0
	v_mov_b32_e32 v2, v0
	v_mov_b64_e32 v[0:1], s[22:23]
	s_and_saveexec_b64 s[20:21], vcc
	s_cbranch_execz .LBB0_888
	v_mov_b32_e32 v0, 0
	global_load_dword v1, v0, s[22:23] offset:-256 sc1
	s_mov_b64 s[44:45], 0
	s_waitcnt vmcnt(0)
	v_cmp_lt_u32_e32 vcc, v1, v2
	s_and_saveexec_b64 s[26:27], vcc
	s_cbranch_execz .LBB0_887
	s_add_u32 s24, s16, 0x4200
	s_addc_u32 s25, s17, 0
	s_mov_b32 s0, 1
	s_mov_b64 s[16:17], 0
	s_branch .LBB0_880

; __device__ __forceinline__ unsigned xb_ld(unsigned* p)              { return __hip_atomic_load(p, __ATOMIC_RELAXED, __HIP_MEMORY_SCOPE_AGENT); }
; #define XB_SPIN(cond, bar) do { unsigned _sp = 0; while (cond) { __builtin_amdgcn_s_sleep(1); \
;     if ((++_sp & 255u) == 0u) { if (xb_ld(&(bar)[XB_TMO])) break; if (_sp > XB_SPIN_CAP) { atomicAdd(&(bar)[XB_TMO], 1u); break; } } } } while (0)
; __device__ __forceinline__ void xcd_barrier(const XcdBarrier& b) {
;     ...
;             else XB_SPIN(xb_ld(&bar[XB_TOPGEN]) == tg, bar);
.LBB0_884:
	global_load_dword v1, v0, s[22:23] offset:-256 sc1
	s_add_i32 s0, s0, 1
	s_mov_b64 s[46:47], -1
	s_waitcnt vmcnt(0)
	v_cmp_ge_u32_e32 vcc, v1, v2
	s_orn2_b64 s[50:51], vcc, exec
	s_branch .LBB0_879

; __device__ __forceinline__ unsigned xb_ld(unsigned* p)              { return __hip_atomic_load(p, __ATOMIC_RELAXED, __HIP_MEMORY_SCOPE_AGENT); }
; __device__ __forceinline__ unsigned xb_add(unsigned* p, unsigned v) { return __hip_atomic_fetch_add(p, v, __ATOMIC_RELAXED, __HIP_MEMORY_SCOPE_AGENT); }
; #define XB_SPIN(cond, bar) do { unsigned _sp = 0; while (cond) { __builtin_amdgcn_s_sleep(1); \
;     if ((++_sp & 255u) == 0u) { if (xb_ld(&(bar)[XB_TMO])) break; if (_sp > XB_SPIN_CAP) { atomicAdd(&(bar)[XB_TMO], 1u); break; } } } } while (0)
; __device__ __forceinline__ void xcd_barrier(const XcdBarrier& b) {
;     ...
;         const unsigned old = xb_add(&bar[XB_XSUB(b.x)], 1u);
;         const unsigned gen = old / nloc;
;         if (old + 1u == (gen + 1u) * nloc) {
;             __builtin_amdgcn_fence(__ATOMIC_RELEASE, "agent");
;             asm volatile("s_waitcnt vmcnt(0)" ::: "memory");
;             const unsigned og = xb_add(&bar[XB_TOP], 1u);
;             const unsigned tg = og / nx;
;             if (og + 1u == (tg + 1u) * nx) xb_add(&bar[XB_TOPGEN], 1u);
;             else XB_SPIN(xb_ld(&bar[XB_TOPGEN]) == tg, bar);
;             __builtin_amdgcn_fence(__ATOMIC_ACQUIRE, "agent");
;             xb_add(&bar[XB_XGEN(b.x)], 1u);
;             asm volatile("s_waitcnt vmcnt(0)" ::: "memory");
;         } else {
;             XB_SPIN(xb_ld(&bar[XB_XGEN(b.x)]) == gen, bar);
.LBB0_1021:
	s_or_b64 exec, exec, s[24:25]
	v_cvt_f32_u32_e32 v4, v2
	s_waitcnt vmcnt(0)
	v_readfirstlane_b32 s0, v3
	v_sub_u32_e32 v3, 0, v2
	v_rcp_iflag_f32_e32 v4, v4
	v_add_u32_e32 v5, s0, v1
	v_mul_f32_e32 v4, 0x4f7ffffe, v4
	v_cvt_u32_f32_e32 v4, v4
	v_mul_lo_u32 v1, v3, v4
	v_mul_hi_u32 v1, v4, v1
	v_add_u32_e32 v1, v4, v1
	v_mul_hi_u32 v1, v5, v1
	v_mul_lo_u32 v3, v1, v2
	v_sub_u32_e32 v3, v5, v3
	v_add_u32_e32 v4, 1, v1
	v_cmp_ge_u32_e32 vcc, v3, v2
	s_nop 1
	v_cndmask_b32_e32 v1, v1, v4, vcc
	v_sub_u32_e32 v4, v3, v2
	v_cndmask_b32_e32 v3, v3, v4, vcc
	v_add_u32_e32 v4, 1, v1
	v_cmp_ge_u32_e32 vcc, v3, v2
	v_add_u32_e32 v3, 1, v5
	s_nop 0
	v_cndmask_b32_e32 v1, v1, v4, vcc
	v_mul_lo_u32 v4, v2, v1
	v_add_u32_e32 v2, v4, v2
	v_cmp_ne_u32_e32 vcc, v3, v2
	s_and_saveexec_b64 s[12:13], vcc
	s_xor_b64 s[22:23], exec, s[12:13]
	s_cbranch_execz .LBB0_1035
	s_waitcnt lgkmcnt(0)
	v_mov_b32_e32 v0, 0x20044
	ds_read_b32 v2, v0
	v_mov_b32_e32 v0, 0x7000
	global_load_dword v0, v0, s[18:19] offset:1024 sc1
	s_add_u32 s42, s18, 0x7400
	s_addc_u32 s43, s19, 0
	s_waitcnt lgkmcnt(0)
	v_mad_u32_u24 v1, v1, v2, v2
	s_waitcnt vmcnt(0)
	v_cmp_lt_u32_e32 vcc, v0, v1
	s_and_saveexec_b64 s[24:25], vcc
	s_cbranch_execz .LBB0_1034
	s_add_u32 s26, s18, 0x4200
	s_addc_u32 s27, s19, 0
	s_mov_b32 s0, 1
	s_mov_b64 s[44:45], 0
	v_mov_b32_e32 v0, 0
	s_branch .LBB0_1025

; __device__ __forceinline__ unsigned xb_ld(unsigned* p)              { return __hip_atomic_load(p, __ATOMIC_RELAXED, __HIP_MEMORY_SCOPE_AGENT); }
; #define XB_SPIN(cond, bar) do { unsigned _sp = 0; while (cond) { __builtin_amdgcn_s_sleep(1); \
;     if ((++_sp & 255u) == 0u) { if (xb_ld(&(bar)[XB_TMO])) break; if (_sp > XB_SPIN_CAP) { atomicAdd(&(bar)[XB_TMO], 1u); break; } } } } while (0)
; __device__ __forceinline__ void xcd_barrier(const XcdBarrier& b) {
;     ...
;             XB_SPIN(xb_ld(&bar[XB_XGEN(b.x)]) == gen, bar);
.LBB0_1029:
	global_load_dword v2, v0, s[42:43] sc1
	s_add_i32 s0, s0, 1
	s_mov_b64 s[50:51], -1
	s_waitcnt vmcnt(0)
	v_cmp_ge_u32_e32 vcc, v2, v1
	s_orn2_b64 s[48:49], vcc, exec
	s_branch .LBB0_1024

; __device__ __forceinline__ unsigned xb_ld(unsigned* p)              { return __hip_atomic_load(p, __ATOMIC_RELAXED, __HIP_MEMORY_SCOPE_AGENT); }
; __device__ __forceinline__ unsigned xb_add(unsigned* p, unsigned v) { return __hip_atomic_fetch_add(p, v, __ATOMIC_RELAXED, __HIP_MEMORY_SCOPE_AGENT); }
; #define XB_SPIN(cond, bar) do { unsigned _sp = 0; while (cond) { __builtin_amdgcn_s_sleep(1); \
;     if ((++_sp & 255u) == 0u) { if (xb_ld(&(bar)[XB_TMO])) break; if (_sp > XB_SPIN_CAP) { atomicAdd(&(bar)[XB_TMO], 1u); break; } } } } while (0)
; __device__ __forceinline__ void xcd_barrier(const XcdBarrier& b) {
;     ...
;         if (old + 1u == (gen + 1u) * nloc) {
;             __builtin_amdgcn_fence(__ATOMIC_RELEASE, "agent");
;             asm volatile("s_waitcnt vmcnt(0)" ::: "memory");
;             const unsigned og = xb_add(&bar[XB_TOP], 1u);
;             const unsigned tg = og / nx;
;             if (og + 1u == (tg + 1u) * nx) xb_add(&bar[XB_TOPGEN], 1u);
;             else XB_SPIN(xb_ld(&bar[XB_TOPGEN]) == tg, bar);
.LBB0_1038:
	s_or_b64 exec, exec, s[24:25]
	v_cvt_f32_u32_e32 v3, v0
	s_waitcnt vmcnt(0)
	v_readfirstlane_b32 s0, v2
	s_add_u32 s24, s18, 0x7500
	s_addc_u32 s25, s19, 0
	v_rcp_iflag_f32_e32 v3, v3
	v_add_u32_e32 v1, s0, v1
	v_add_u32_e32 v4, 1, v1
	s_mov_b64 s[26:27], -1
	v_mul_f32_e32 v2, 0x4f7ffffe, v3
	v_cvt_u32_f32_e32 v2, v2
	v_sub_u32_e32 v3, 0, v0
	v_mul_lo_u32 v3, v3, v2
	v_mul_hi_u32 v3, v2, v3
	v_add_u32_e32 v2, v2, v3
	v_mul_hi_u32 v2, v1, v2
	v_mul_lo_u32 v3, v2, v0
	v_sub_u32_e32 v1, v1, v3
	v_add_u32_e32 v5, 1, v2
	v_cmp_ge_u32_e32 vcc, v1, v0
	v_sub_u32_e32 v3, v1, v0
	s_nop 0
	v_cndmask_b32_e32 v2, v2, v5, vcc
	v_cndmask_b32_e32 v1, v1, v3, vcc
	v_add_u32_e32 v3, 1, v2
	v_cmp_ge_u32_e32 vcc, v1, v0
	s_nop 1
	v_cndmask_b32_e32 v2, v2, v3, vcc
	v_mul_lo_u32 v1, v0, v2
	v_add_u32_e32 v0, v1, v0
	v_cmp_ne_u32_e32 vcc, v4, v0
	v_mov_b32_e32 v2, v0
	v_mov_b64_e32 v[0:1], s[24:25]
	s_and_saveexec_b64 s[22:23], vcc
	s_cbranch_execz .LBB0_1050
	v_mov_b32_e32 v0, 0
	global_load_dword v1, v0, s[24:25] offset:-256 sc1
	s_mov_b64 s[44:45], 0
	s_waitcnt vmcnt(0)
	v_cmp_lt_u32_e32 vcc, v1, v2
	s_and_saveexec_b64 s[42:43], vcc
	s_cbranch_execz .LBB0_1049
	s_add_u32 s26, s18, 0x4200
	s_addc_u32 s27, s19, 0
	s_mov_b32 s0, 1
	s_mov_b64 s[18:19], 0
	s_branch .LBB0_1042

; __device__ __forceinline__ unsigned xb_ld(unsigned* p)              { return __hip_atomic_load(p, __ATOMIC_RELAXED, __HIP_MEMORY_SCOPE_AGENT); }
; #define XB_SPIN(cond, bar) do { unsigned _sp = 0; while (cond) { __builtin_amdgcn_s_sleep(1); \
;     if ((++_sp & 255u) == 0u) { if (xb_ld(&(bar)[XB_TMO])) break; if (_sp > XB_SPIN_CAP) { atomicAdd(&(bar)[XB_TMO], 1u); break; } } } } while (0)
; __device__ __forceinline__ void xcd_barrier(const XcdBarrier& b) {
;     ...
;             else XB_SPIN(xb_ld(&bar[XB_TOPGEN]) == tg, bar);
.LBB0_1046:
	global_load_dword v1, v0, s[24:25] offset:-256 sc1
	s_add_i32 s0, s0, 1
	s_mov_b64 s[46:47], -1
	s_waitcnt vmcnt(0)
	v_cmp_ge_u32_e32 vcc, v1, v2
	s_orn2_b64 s[50:51], vcc, exec
	s_branch .LBB0_1041

; __device__ __forceinline__ unsigned xb_ld(unsigned* p)              { return __hip_atomic_load(p, __ATOMIC_RELAXED, __HIP_MEMORY_SCOPE_AGENT); }
; __device__ __forceinline__ unsigned xb_add(unsigned* p, unsigned v) { return __hip_atomic_fetch_add(p, v, __ATOMIC_RELAXED, __HIP_MEMORY_SCOPE_AGENT); }
; #define XB_SPIN(cond, bar) do { unsigned _sp = 0; while (cond) { __builtin_amdgcn_s_sleep(1); \
;     if ((++_sp & 255u) == 0u) { if (xb_ld(&(bar)[XB_TMO])) break; if (_sp > XB_SPIN_CAP) { atomicAdd(&(bar)[XB_TMO], 1u); break; } } } } while (0)
; __device__ __forceinline__ void xcd_barrier(const XcdBarrier& b) {
;     ...
;         const unsigned old = xb_add(&bar[XB_XSUB(b.x)], 1u);
;         const unsigned gen = old / nloc;
;         if (old + 1u == (gen + 1u) * nloc) {
;             __builtin_amdgcn_fence(__ATOMIC_RELEASE, "agent");
;             asm volatile("s_waitcnt vmcnt(0)" ::: "memory");
;             const unsigned og = xb_add(&bar[XB_TOP], 1u);
;             const unsigned tg = og / nx;
;             if (og + 1u == (tg + 1u) * nx) xb_add(&bar[XB_TOPGEN], 1u);
;             else XB_SPIN(xb_ld(&bar[XB_TOPGEN]) == tg, bar);
;             __builtin_amdgcn_fence(__ATOMIC_ACQUIRE, "agent");
;             xb_add(&bar[XB_XGEN(b.x)], 1u);
;             asm volatile("s_waitcnt vmcnt(0)" ::: "memory");
;         } else {
;             XB_SPIN(xb_ld(&bar[XB_XGEN(b.x)]) == gen, bar);
.LBB0_1269:
	s_or_b64 exec, exec, s[22:23]
	v_cvt_f32_u32_e32 v4, v2
	s_waitcnt vmcnt(0)
	v_readfirstlane_b32 s0, v3
	v_sub_u32_e32 v3, 0, v2
	v_rcp_iflag_f32_e32 v4, v4
	v_add_u32_e32 v5, s0, v1
	v_mul_f32_e32 v4, 0x4f7ffffe, v4
	v_cvt_u32_f32_e32 v4, v4
	v_mul_lo_u32 v1, v3, v4
	v_mul_hi_u32 v1, v4, v1
	v_add_u32_e32 v1, v4, v1
	v_mul_hi_u32 v1, v5, v1
	v_mul_lo_u32 v3, v1, v2
	v_sub_u32_e32 v3, v5, v3
	v_add_u32_e32 v4, 1, v1
	v_cmp_ge_u32_e32 vcc, v3, v2
	s_nop 1
	v_cndmask_b32_e32 v1, v1, v4, vcc
	v_sub_u32_e32 v4, v3, v2
	v_cndmask_b32_e32 v3, v3, v4, vcc
	v_add_u32_e32 v4, 1, v1
	v_cmp_ge_u32_e32 vcc, v3, v2
	v_add_u32_e32 v3, 1, v5
	s_nop 0
	v_cndmask_b32_e32 v1, v1, v4, vcc
	v_mul_lo_u32 v4, v2, v1
	v_add_u32_e32 v2, v4, v2
	v_cmp_ne_u32_e32 vcc, v3, v2
	s_and_saveexec_b64 s[12:13], vcc
	s_xor_b64 s[20:21], exec, s[12:13]
	s_cbranch_execz .LBB0_1283
	s_waitcnt lgkmcnt(0)
	v_mov_b32_e32 v0, 0x20044
	ds_read_b32 v2, v0
	v_mov_b32_e32 v0, 0x7000
	global_load_dword v0, v0, s[16:17] offset:1024 sc1
	s_add_u32 s26, s16, 0x7400
	s_addc_u32 s27, s17, 0
	s_waitcnt lgkmcnt(0)
	v_mad_u32_u24 v1, v1, v2, v2
	s_waitcnt vmcnt(0)
	v_cmp_lt_u32_e32 vcc, v0, v1
	s_and_saveexec_b64 s[22:23], vcc
	s_cbranch_execz .LBB0_1282
	s_add_u32 s24, s16, 0x4200
	s_addc_u32 s25, s17, 0
	s_mov_b32 s0, 1
	s_mov_b64 s[42:43], 0
	v_mov_b32_e32 v0, 0
	s_branch .LBB0_1273

; __device__ __forceinline__ unsigned xb_ld(unsigned* p)              { return __hip_atomic_load(p, __ATOMIC_RELAXED, __HIP_MEMORY_SCOPE_AGENT); }
; #define XB_SPIN(cond, bar) do { unsigned _sp = 0; while (cond) { __builtin_amdgcn_s_sleep(1); \
;     if ((++_sp & 255u) == 0u) { if (xb_ld(&(bar)[XB_TMO])) break; if (_sp > XB_SPIN_CAP) { atomicAdd(&(bar)[XB_TMO], 1u); break; } } } } while (0)
; __device__ __forceinline__ void xcd_barrier(const XcdBarrier& b) {
;     ...
;             XB_SPIN(xb_ld(&bar[XB_XGEN(b.x)]) == gen, bar);
.LBB0_1277:
	global_load_dword v2, v0, s[26:27] sc1
	s_add_i32 s0, s0, 1
	s_mov_b64 s[48:49], -1
	s_waitcnt vmcnt(0)
	v_cmp_ge_u32_e32 vcc, v2, v1
	s_orn2_b64 s[46:47], vcc, exec
	s_branch .LBB0_1272

; __device__ __forceinline__ unsigned xb_ld(unsigned* p)              { return __hip_atomic_load(p, __ATOMIC_RELAXED, __HIP_MEMORY_SCOPE_AGENT); }
; __device__ __forceinline__ unsigned xb_add(unsigned* p, unsigned v) { return __hip_atomic_fetch_add(p, v, __ATOMIC_RELAXED, __HIP_MEMORY_SCOPE_AGENT); }
; #define XB_SPIN(cond, bar) do { unsigned _sp = 0; while (cond) { __builtin_amdgcn_s_sleep(1); \
;     if ((++_sp & 255u) == 0u) { if (xb_ld(&(bar)[XB_TMO])) break; if (_sp > XB_SPIN_CAP) { atomicAdd(&(bar)[XB_TMO], 1u); break; } } } } while (0)
; __device__ __forceinline__ void xcd_barrier(const XcdBarrier& b) {
;     ...
;         if (old + 1u == (gen + 1u) * nloc) {
;             __builtin_amdgcn_fence(__ATOMIC_RELEASE, "agent");
;             asm volatile("s_waitcnt vmcnt(0)" ::: "memory");
;             const unsigned og = xb_add(&bar[XB_TOP], 1u);
;             const unsigned tg = og / nx;
;             if (og + 1u == (tg + 1u) * nx) xb_add(&bar[XB_TOPGEN], 1u);
;             else XB_SPIN(xb_ld(&bar[XB_TOPGEN]) == tg, bar);
.LBB0_1286:
	s_or_b64 exec, exec, s[22:23]
	v_cvt_f32_u32_e32 v3, v0
	s_waitcnt vmcnt(0)
	v_readfirstlane_b32 s0, v2
	s_add_u32 s22, s16, 0x7500
	s_addc_u32 s23, s17, 0
	v_rcp_iflag_f32_e32 v3, v3
	v_add_u32_e32 v1, s0, v1
	v_add_u32_e32 v4, 1, v1
	s_mov_b64 s[24:25], -1
	v_mul_f32_e32 v2, 0x4f7ffffe, v3
	v_cvt_u32_f32_e32 v2, v2
	v_sub_u32_e32 v3, 0, v0
	v_mul_lo_u32 v3, v3, v2
	v_mul_hi_u32 v3, v2, v3
	v_add_u32_e32 v2, v2, v3
	v_mul_hi_u32 v2, v1, v2
	v_mul_lo_u32 v3, v2, v0
	v_sub_u32_e32 v1, v1, v3
	v_add_u32_e32 v5, 1, v2
	v_cmp_ge_u32_e32 vcc, v1, v0
	v_sub_u32_e32 v3, v1, v0
	s_nop 0
	v_cndmask_b32_e32 v2, v2, v5, vcc
	v_cndmask_b32_e32 v1, v1, v3, vcc
	v_add_u32_e32 v3, 1, v2
	v_cmp_ge_u32_e32 vcc, v1, v0
	s_nop 1
	v_cndmask_b32_e32 v2, v2, v3, vcc
	v_mul_lo_u32 v1, v0, v2
	v_add_u32_e32 v0, v1, v0
	v_cmp_ne_u32_e32 vcc, v4, v0
	v_mov_b32_e32 v2, v0
	v_mov_b64_e32 v[0:1], s[22:23]
	s_and_saveexec_b64 s[20:21], vcc
	s_cbranch_execz .LBB0_1298
	v_mov_b32_e32 v0, 0
	global_load_dword v1, v0, s[22:23] offset:-256 sc1
	s_mov_b64 s[42:43], 0
	s_waitcnt vmcnt(0)
	v_cmp_lt_u32_e32 vcc, v1, v2
	s_and_saveexec_b64 s[26:27], vcc
	s_cbranch_execz .LBB0_1297
	s_add_u32 s24, s16, 0x4200
	s_addc_u32 s25, s17, 0
	s_mov_b32 s0, 1
	s_mov_b64 s[16:17], 0
	s_branch .LBB0_1290

; __device__ __forceinline__ unsigned xb_ld(unsigned* p)              { return __hip_atomic_load(p, __ATOMIC_RELAXED, __HIP_MEMORY_SCOPE_AGENT); }
; #define XB_SPIN(cond, bar) do { unsigned _sp = 0; while (cond) { __builtin_amdgcn_s_sleep(1); \
;     if ((++_sp & 255u) == 0u) { if (xb_ld(&(bar)[XB_TMO])) break; if (_sp > XB_SPIN_CAP) { atomicAdd(&(bar)[XB_TMO], 1u); break; } } } } while (0)
; __device__ __forceinline__ void xcd_barrier(const XcdBarrier& b) {
;     ...
;             else XB_SPIN(xb_ld(&bar[XB_TOPGEN]) == tg, bar);
.LBB0_1294:
	global_load_dword v1, v0, s[22:23] offset:-256 sc1
	s_add_i32 s0, s0, 1
	s_mov_b64 s[44:45], -1
	s_waitcnt vmcnt(0)
	v_cmp_ge_u32_e32 vcc, v1, v2
	s_orn2_b64 s[48:49], vcc, exec
	s_branch .LBB0_1289

; __device__ __forceinline__ unsigned xb_ld(unsigned* p)              { return __hip_atomic_load(p, __ATOMIC_RELAXED, __HIP_MEMORY_SCOPE_AGENT); }
; __device__ __forceinline__ unsigned xb_add(unsigned* p, unsigned v) { return __hip_atomic_fetch_add(p, v, __ATOMIC_RELAXED, __HIP_MEMORY_SCOPE_AGENT); }
; #define XB_SPIN(cond, bar) do { unsigned _sp = 0; while (cond) { __builtin_amdgcn_s_sleep(1); \
;     if ((++_sp & 255u) == 0u) { if (xb_ld(&(bar)[XB_TMO])) break; if (_sp > XB_SPIN_CAP) { atomicAdd(&(bar)[XB_TMO], 1u); break; } } } } while (0)
; __device__ __forceinline__ void xcd_barrier(const XcdBarrier& b) {
;     ...
;         const unsigned old = xb_add(&bar[XB_XSUB(b.x)], 1u);
;         const unsigned gen = old / nloc;
;         if (old + 1u == (gen + 1u) * nloc) {
;             __builtin_amdgcn_fence(__ATOMIC_RELEASE, "agent");
;             asm volatile("s_waitcnt vmcnt(0)" ::: "memory");
;             const unsigned og = xb_add(&bar[XB_TOP], 1u);
;             const unsigned tg = og / nx;
;             if (og + 1u == (tg + 1u) * nx) xb_add(&bar[XB_TOPGEN], 1u);
;             else XB_SPIN(xb_ld(&bar[XB_TOPGEN]) == tg, bar);
;             __builtin_amdgcn_fence(__ATOMIC_ACQUIRE, "agent");
;             xb_add(&bar[XB_XGEN(b.x)], 1u);
;             asm volatile("s_waitcnt vmcnt(0)" ::: "memory");
;         } else {
;             XB_SPIN(xb_ld(&bar[XB_XGEN(b.x)]) == gen, bar);
.LBB0_1451:
	s_or_b64 exec, exec, s[20:21]
	v_cvt_f32_u32_e32 v4, v2
	s_waitcnt vmcnt(0)
	v_readfirstlane_b32 s0, v3
	v_sub_u32_e32 v3, 0, v2
	v_rcp_iflag_f32_e32 v4, v4
	v_add_u32_e32 v5, s0, v1
	v_mul_f32_e32 v4, 0x4f7ffffe, v4
	v_cvt_u32_f32_e32 v4, v4
	v_mul_lo_u32 v1, v3, v4
	v_mul_hi_u32 v1, v4, v1
	v_add_u32_e32 v1, v4, v1
	v_mul_hi_u32 v1, v5, v1
	v_mul_lo_u32 v3, v1, v2
	v_sub_u32_e32 v3, v5, v3
	v_add_u32_e32 v4, 1, v1
	v_cmp_ge_u32_e32 vcc, v3, v2
	s_nop 1
	v_cndmask_b32_e32 v1, v1, v4, vcc
	v_sub_u32_e32 v4, v3, v2
	v_cndmask_b32_e32 v3, v3, v4, vcc
	v_add_u32_e32 v4, 1, v1
	v_cmp_ge_u32_e32 vcc, v3, v2
	v_add_u32_e32 v3, 1, v5
	s_nop 0
	v_cndmask_b32_e32 v1, v1, v4, vcc
	v_mul_lo_u32 v4, v2, v1
	v_add_u32_e32 v2, v4, v2
	v_cmp_ne_u32_e32 vcc, v3, v2
	s_and_saveexec_b64 s[6:7], vcc
	s_xor_b64 s[18:19], exec, s[6:7]
	s_cbranch_execz .LBB0_1465
	s_waitcnt lgkmcnt(0)
	v_mov_b32_e32 v0, 0x20044
	ds_read_b32 v2, v0
	v_mov_b32_e32 v0, 0x7000
	global_load_dword v0, v0, s[14:15] offset:1024 sc1
	s_add_u32 s24, s14, 0x7400
	s_addc_u32 s25, s15, 0
	s_waitcnt lgkmcnt(0)
	v_mad_u32_u24 v1, v1, v2, v2
	s_waitcnt vmcnt(0)
	v_cmp_lt_u32_e32 vcc, v0, v1
	s_and_saveexec_b64 s[20:21], vcc
	s_cbranch_execz .LBB0_1464
	s_add_u32 s22, s14, 0x4200
	s_addc_u32 s23, s15, 0
	s_mov_b32 s0, 1
	s_mov_b64 s[26:27], 0
	v_mov_b32_e32 v0, 0
	s_branch .LBB0_1455

; __device__ __forceinline__ unsigned xb_ld(unsigned* p)              { return __hip_atomic_load(p, __ATOMIC_RELAXED, __HIP_MEMORY_SCOPE_AGENT); }
; #define XB_SPIN(cond, bar) do { unsigned _sp = 0; while (cond) { __builtin_amdgcn_s_sleep(1); \
;     if ((++_sp & 255u) == 0u) { if (xb_ld(&(bar)[XB_TMO])) break; if (_sp > XB_SPIN_CAP) { atomicAdd(&(bar)[XB_TMO], 1u); break; } } } } while (0)
; __device__ __forceinline__ void xcd_barrier(const XcdBarrier& b) {
;     ...
;             XB_SPIN(xb_ld(&bar[XB_XGEN(b.x)]) == gen, bar);
.LBB0_1459:
	global_load_dword v2, v0, s[24:25] sc1
	s_add_i32 s0, s0, 1
	s_mov_b64 s[46:47], -1
	s_waitcnt vmcnt(0)
	v_cmp_ge_u32_e32 vcc, v2, v1
	s_orn2_b64 s[44:45], vcc, exec
	s_branch .LBB0_1454

; __device__ __forceinline__ unsigned xb_ld(unsigned* p)              { return __hip_atomic_load(p, __ATOMIC_RELAXED, __HIP_MEMORY_SCOPE_AGENT); }
; __device__ __forceinline__ unsigned xb_add(unsigned* p, unsigned v) { return __hip_atomic_fetch_add(p, v, __ATOMIC_RELAXED, __HIP_MEMORY_SCOPE_AGENT); }
; #define XB_SPIN(cond, bar) do { unsigned _sp = 0; while (cond) { __builtin_amdgcn_s_sleep(1); \
;     if ((++_sp & 255u) == 0u) { if (xb_ld(&(bar)[XB_TMO])) break; if (_sp > XB_SPIN_CAP) { atomicAdd(&(bar)[XB_TMO], 1u); break; } } } } while (0)
; __device__ __forceinline__ void xcd_barrier(const XcdBarrier& b) {
;     ...
;         if (old + 1u == (gen + 1u) * nloc) {
;             __builtin_amdgcn_fence(__ATOMIC_RELEASE, "agent");
;             asm volatile("s_waitcnt vmcnt(0)" ::: "memory");
;             const unsigned og = xb_add(&bar[XB_TOP], 1u);
;             const unsigned tg = og / nx;
;             if (og + 1u == (tg + 1u) * nx) xb_add(&bar[XB_TOPGEN], 1u);
;             else XB_SPIN(xb_ld(&bar[XB_TOPGEN]) == tg, bar);
.LBB0_1468:
	s_or_b64 exec, exec, s[20:21]
	v_cvt_f32_u32_e32 v3, v0
	s_waitcnt vmcnt(0)
	v_readfirstlane_b32 s0, v2
	s_add_u32 s20, s14, 0x7500
	s_addc_u32 s21, s15, 0
	v_rcp_iflag_f32_e32 v3, v3
	v_add_u32_e32 v1, s0, v1
	v_add_u32_e32 v4, 1, v1
	s_mov_b64 s[22:23], -1
	v_mul_f32_e32 v2, 0x4f7ffffe, v3
	v_cvt_u32_f32_e32 v2, v2
	v_sub_u32_e32 v3, 0, v0
	v_mul_lo_u32 v3, v3, v2
	v_mul_hi_u32 v3, v2, v3
	v_add_u32_e32 v2, v2, v3
	v_mul_hi_u32 v2, v1, v2
	v_mul_lo_u32 v3, v2, v0
	v_sub_u32_e32 v1, v1, v3
	v_add_u32_e32 v5, 1, v2
	v_cmp_ge_u32_e32 vcc, v1, v0
	v_sub_u32_e32 v3, v1, v0
	s_nop 0
	v_cndmask_b32_e32 v2, v2, v5, vcc
	v_cndmask_b32_e32 v1, v1, v3, vcc
	v_add_u32_e32 v3, 1, v2
	v_cmp_ge_u32_e32 vcc, v1, v0
	s_nop 1
	v_cndmask_b32_e32 v2, v2, v3, vcc
	v_mul_lo_u32 v1, v0, v2
	v_add_u32_e32 v0, v1, v0
	v_cmp_ne_u32_e32 vcc, v4, v0
	v_mov_b32_e32 v2, v0
	v_mov_b64_e32 v[0:1], s[20:21]
	s_and_saveexec_b64 s[18:19], vcc
	s_cbranch_execz .LBB0_1480
	v_mov_b32_e32 v0, 0
	global_load_dword v1, v0, s[20:21] offset:-256 sc1
	s_mov_b64 s[26:27], 0
	s_waitcnt vmcnt(0)
	v_cmp_lt_u32_e32 vcc, v1, v2
	s_and_saveexec_b64 s[24:25], vcc
	s_cbranch_execz .LBB0_1479
	s_add_u32 s22, s14, 0x4200
	s_addc_u32 s23, s15, 0
	s_mov_b32 s0, 1
	s_mov_b64 s[14:15], 0
	s_branch .LBB0_1472

; __device__ __forceinline__ unsigned xb_ld(unsigned* p)              { return __hip_atomic_load(p, __ATOMIC_RELAXED, __HIP_MEMORY_SCOPE_AGENT); }
; #define XB_SPIN(cond, bar) do { unsigned _sp = 0; while (cond) { __builtin_amdgcn_s_sleep(1); \
;     if ((++_sp & 255u) == 0u) { if (xb_ld(&(bar)[XB_TMO])) break; if (_sp > XB_SPIN_CAP) { atomicAdd(&(bar)[XB_TMO], 1u); break; } } } } while (0)
; __device__ __forceinline__ void xcd_barrier(const XcdBarrier& b) {
;     ...
;             else XB_SPIN(xb_ld(&bar[XB_TOPGEN]) == tg, bar);
.LBB0_1476:
	global_load_dword v1, v0, s[20:21] offset:-256 sc1
	s_add_i32 s0, s0, 1
	s_mov_b64 s[42:43], -1
	s_waitcnt vmcnt(0)
	v_cmp_ge_u32_e32 vcc, v1, v2
	s_orn2_b64 s[46:47], vcc, exec
	s_branch .LBB0_1471

; __device__ __forceinline__ unsigned xb_ld(unsigned* p)              { return __hip_atomic_load(p, __ATOMIC_RELAXED, __HIP_MEMORY_SCOPE_AGENT); }
; __device__ __forceinline__ unsigned xb_add(unsigned* p, unsigned v) { return __hip_atomic_fetch_add(p, v, __ATOMIC_RELAXED, __HIP_MEMORY_SCOPE_AGENT); }
; #define XB_SPIN(cond, bar) do { unsigned _sp = 0; while (cond) { __builtin_amdgcn_s_sleep(1); \
;     if ((++_sp & 255u) == 0u) { if (xb_ld(&(bar)[XB_TMO])) break; if (_sp > XB_SPIN_CAP) { atomicAdd(&(bar)[XB_TMO], 1u); break; } } } } while (0)
; __device__ __forceinline__ void xcd_barrier(const XcdBarrier& b) {
;     ...
;         const unsigned old = xb_add(&bar[XB_XSUB(b.x)], 1u);
;         const unsigned gen = old / nloc;
;         if (old + 1u == (gen + 1u) * nloc) {
;             __builtin_amdgcn_fence(__ATOMIC_RELEASE, "agent");
;             asm volatile("s_waitcnt vmcnt(0)" ::: "memory");
;             const unsigned og = xb_add(&bar[XB_TOP], 1u);
;             const unsigned tg = og / nx;
;             if (og + 1u == (tg + 1u) * nx) xb_add(&bar[XB_TOPGEN], 1u);
;             else XB_SPIN(xb_ld(&bar[XB_TOPGEN]) == tg, bar);
;             __builtin_amdgcn_fence(__ATOMIC_ACQUIRE, "agent");
;             xb_add(&bar[XB_XGEN(b.x)], 1u);
;             asm volatile("s_waitcnt vmcnt(0)" ::: "memory");
;         } else {
;             XB_SPIN(xb_ld(&bar[XB_XGEN(b.x)]) == gen, bar);
.LBB0_1797:
	s_or_b64 exec, exec, s[18:19]
	v_cvt_f32_u32_e32 v4, v2
	s_waitcnt vmcnt(0)
	v_readfirstlane_b32 s0, v3
	v_sub_u32_e32 v3, 0, v2
	v_rcp_iflag_f32_e32 v4, v4
	v_add_u32_e32 v5, s0, v1
	v_mul_f32_e32 v4, 0x4f7ffffe, v4
	v_cvt_u32_f32_e32 v4, v4
	v_mul_lo_u32 v1, v3, v4
	v_mul_hi_u32 v1, v4, v1
	v_add_u32_e32 v1, v4, v1
	v_mul_hi_u32 v1, v5, v1
	v_mul_lo_u32 v3, v1, v2
	v_sub_u32_e32 v3, v5, v3
	v_add_u32_e32 v4, 1, v1
	v_cmp_ge_u32_e32 vcc, v3, v2
	s_nop 1
	v_cndmask_b32_e32 v1, v1, v4, vcc
	v_sub_u32_e32 v4, v3, v2
	v_cndmask_b32_e32 v3, v3, v4, vcc
	v_add_u32_e32 v4, 1, v1
	v_cmp_ge_u32_e32 vcc, v3, v2
	v_add_u32_e32 v3, 1, v5
	s_nop 0
	v_cndmask_b32_e32 v1, v1, v4, vcc
	v_mul_lo_u32 v4, v2, v1
	v_add_u32_e32 v2, v4, v2
	v_cmp_ne_u32_e32 vcc, v3, v2
	s_and_saveexec_b64 s[12:13], vcc
	s_xor_b64 s[16:17], exec, s[12:13]
	s_cbranch_execz .LBB0_1811
	s_waitcnt lgkmcnt(0)
	v_mov_b32_e32 v0, 0x20044
	ds_read_b32 v2, v0
	v_mov_b32_e32 v0, 0x7000
	global_load_dword v0, v0, s[8:9] offset:1024 sc1
	s_add_u32 s22, s8, 0x7400
	s_addc_u32 s23, s9, 0
	s_waitcnt lgkmcnt(0)
	v_mad_u32_u24 v1, v1, v2, v2
	s_waitcnt vmcnt(0)
	v_cmp_lt_u32_e32 vcc, v0, v1
	s_and_saveexec_b64 s[18:19], vcc
	s_cbranch_execz .LBB0_1810
	s_add_u32 s20, s8, 0x4200
	s_addc_u32 s21, s9, 0
	s_mov_b32 s0, 1
	s_mov_b64 s[24:25], 0
	v_mov_b32_e32 v0, 0
	s_branch .LBB0_1801

; __device__ __forceinline__ unsigned xb_ld(unsigned* p)              { return __hip_atomic_load(p, __ATOMIC_RELAXED, __HIP_MEMORY_SCOPE_AGENT); }
; #define XB_SPIN(cond, bar) do { unsigned _sp = 0; while (cond) { __builtin_amdgcn_s_sleep(1); \
;     if ((++_sp & 255u) == 0u) { if (xb_ld(&(bar)[XB_TMO])) break; if (_sp > XB_SPIN_CAP) { atomicAdd(&(bar)[XB_TMO], 1u); break; } } } } while (0)
; __device__ __forceinline__ void xcd_barrier(const XcdBarrier& b) {
;     ...
;             XB_SPIN(xb_ld(&bar[XB_XGEN(b.x)]) == gen, bar);
.LBB0_1805:
	global_load_dword v2, v0, s[22:23] sc1
	s_add_i32 s0, s0, 1
	s_mov_b64 s[44:45], -1
	s_waitcnt vmcnt(0)
	v_cmp_ge_u32_e32 vcc, v2, v1
	s_orn2_b64 s[42:43], vcc, exec
	s_branch .LBB0_1800

; __device__ __forceinline__ unsigned xb_ld(unsigned* p)              { return __hip_atomic_load(p, __ATOMIC_RELAXED, __HIP_MEMORY_SCOPE_AGENT); }
; __device__ __forceinline__ unsigned xb_add(unsigned* p, unsigned v) { return __hip_atomic_fetch_add(p, v, __ATOMIC_RELAXED, __HIP_MEMORY_SCOPE_AGENT); }
; #define XB_SPIN(cond, bar) do { unsigned _sp = 0; while (cond) { __builtin_amdgcn_s_sleep(1); \
;     if ((++_sp & 255u) == 0u) { if (xb_ld(&(bar)[XB_TMO])) break; if (_sp > XB_SPIN_CAP) { atomicAdd(&(bar)[XB_TMO], 1u); break; } } } } while (0)
; __device__ __forceinline__ void xcd_barrier(const XcdBarrier& b) {
;     ...
;         if (old + 1u == (gen + 1u) * nloc) {
;             __builtin_amdgcn_fence(__ATOMIC_RELEASE, "agent");
;             asm volatile("s_waitcnt vmcnt(0)" ::: "memory");
;             const unsigned og = xb_add(&bar[XB_TOP], 1u);
;             const unsigned tg = og / nx;
;             if (og + 1u == (tg + 1u) * nx) xb_add(&bar[XB_TOPGEN], 1u);
;             else XB_SPIN(xb_ld(&bar[XB_TOPGEN]) == tg, bar);
.LBB0_1814:
	s_or_b64 exec, exec, s[18:19]
	v_cvt_f32_u32_e32 v3, v0
	s_waitcnt vmcnt(0)
	v_readfirstlane_b32 s0, v2
	s_add_u32 s18, s8, 0x7500
	s_addc_u32 s19, s9, 0
	v_rcp_iflag_f32_e32 v3, v3
	v_add_u32_e32 v1, s0, v1
	v_add_u32_e32 v4, 1, v1
	s_mov_b64 s[20:21], -1
	v_mul_f32_e32 v2, 0x4f7ffffe, v3
	v_cvt_u32_f32_e32 v2, v2
	v_sub_u32_e32 v3, 0, v0
	v_mul_lo_u32 v3, v3, v2
	v_mul_hi_u32 v3, v2, v3
	v_add_u32_e32 v2, v2, v3
	v_mul_hi_u32 v2, v1, v2
	v_mul_lo_u32 v3, v2, v0
	v_sub_u32_e32 v1, v1, v3
	v_add_u32_e32 v5, 1, v2
	v_cmp_ge_u32_e32 vcc, v1, v0
	v_sub_u32_e32 v3, v1, v0
	s_nop 0
	v_cndmask_b32_e32 v2, v2, v5, vcc
	v_cndmask_b32_e32 v1, v1, v3, vcc
	v_add_u32_e32 v3, 1, v2
	v_cmp_ge_u32_e32 vcc, v1, v0
	s_nop 1
	v_cndmask_b32_e32 v2, v2, v3, vcc
	v_mul_lo_u32 v1, v0, v2
	v_add_u32_e32 v0, v1, v0
	v_cmp_ne_u32_e32 vcc, v4, v0
	v_mov_b32_e32 v2, v0
	v_mov_b64_e32 v[0:1], s[18:19]
	s_and_saveexec_b64 s[16:17], vcc
	s_cbranch_execz .LBB0_1826
	v_mov_b32_e32 v0, 0
	global_load_dword v1, v0, s[18:19] offset:-256 sc1
	s_mov_b64 s[24:25], 0
	s_waitcnt vmcnt(0)
	v_cmp_lt_u32_e32 vcc, v1, v2
	s_and_saveexec_b64 s[22:23], vcc
	s_cbranch_execz .LBB0_1825
	s_add_u32 s20, s8, 0x4200
	s_addc_u32 s21, s9, 0
	s_mov_b32 s0, 1
	s_mov_b64 s[8:9], 0
	s_branch .LBB0_1818

; __device__ __forceinline__ unsigned xb_ld(unsigned* p)              { return __hip_atomic_load(p, __ATOMIC_RELAXED, __HIP_MEMORY_SCOPE_AGENT); }
; #define XB_SPIN(cond, bar) do { unsigned _sp = 0; while (cond) { __builtin_amdgcn_s_sleep(1); \
;     if ((++_sp & 255u) == 0u) { if (xb_ld(&(bar)[XB_TMO])) break; if (_sp > XB_SPIN_CAP) { atomicAdd(&(bar)[XB_TMO], 1u); break; } } } } while (0)
; __device__ __forceinline__ void xcd_barrier(const XcdBarrier& b) {
;     ...
;             else XB_SPIN(xb_ld(&bar[XB_TOPGEN]) == tg, bar);
.LBB0_1822:
	global_load_dword v1, v0, s[18:19] offset:-256 sc1
	s_add_i32 s0, s0, 1
	s_mov_b64 s[26:27], -1
	s_waitcnt vmcnt(0)
	v_cmp_ge_u32_e32 vcc, v1, v2
	s_orn2_b64 s[44:45], vcc, exec
	s_branch .LBB0_1817

; __device__ __forceinline__ unsigned xb_ld(unsigned* p)              { return __hip_atomic_load(p, __ATOMIC_RELAXED, __HIP_MEMORY_SCOPE_AGENT); }
; __device__ __forceinline__ unsigned xb_add(unsigned* p, unsigned v) { return __hip_atomic_fetch_add(p, v, __ATOMIC_RELAXED, __HIP_MEMORY_SCOPE_AGENT); }
; #define XB_SPIN(cond, bar) do { unsigned _sp = 0; while (cond) { __builtin_amdgcn_s_sleep(1); \
;     if ((++_sp & 255u) == 0u) { if (xb_ld(&(bar)[XB_TMO])) break; if (_sp > XB_SPIN_CAP) { atomicAdd(&(bar)[XB_TMO], 1u); break; } } } } while (0)
; __device__ __forceinline__ void xcd_barrier(const XcdBarrier& b) {
;     ...
;         const unsigned old = xb_add(&bar[XB_XSUB(b.x)], 1u);
;         const unsigned gen = old / nloc;
;         if (old + 1u == (gen + 1u) * nloc) {
;             __builtin_amdgcn_fence(__ATOMIC_RELEASE, "agent");
;             asm volatile("s_waitcnt vmcnt(0)" ::: "memory");
;             const unsigned og = xb_add(&bar[XB_TOP], 1u);
;             const unsigned tg = og / nx;
;             if (og + 1u == (tg + 1u) * nx) xb_add(&bar[XB_TOPGEN], 1u);
;             else XB_SPIN(xb_ld(&bar[XB_TOPGEN]) == tg, bar);
;             __builtin_amdgcn_fence(__ATOMIC_ACQUIRE, "agent");
;             xb_add(&bar[XB_XGEN(b.x)], 1u);
;             asm volatile("s_waitcnt vmcnt(0)" ::: "memory");
;         } else {
;             XB_SPIN(xb_ld(&bar[XB_XGEN(b.x)]) == gen, bar);
.LBB0_1903:
	s_or_b64 exec, exec, s[16:17]
	v_cvt_f32_u32_e32 v4, v2
	s_waitcnt vmcnt(0)
	v_readfirstlane_b32 s0, v3
	v_sub_u32_e32 v3, 0, v2
	v_rcp_iflag_f32_e32 v4, v4
	v_add_u32_e32 v5, s0, v1
	v_mul_f32_e32 v4, 0x4f7ffffe, v4
	v_cvt_u32_f32_e32 v4, v4
	v_mul_lo_u32 v1, v3, v4
	v_mul_hi_u32 v1, v4, v1
	v_add_u32_e32 v1, v4, v1
	v_mul_hi_u32 v1, v5, v1
	v_mul_lo_u32 v3, v1, v2
	v_sub_u32_e32 v3, v5, v3
	v_add_u32_e32 v4, 1, v1
	v_cmp_ge_u32_e32 vcc, v3, v2
	s_nop 1
	v_cndmask_b32_e32 v1, v1, v4, vcc
	v_sub_u32_e32 v4, v3, v2
	v_cndmask_b32_e32 v3, v3, v4, vcc
	v_add_u32_e32 v4, 1, v1
	v_cmp_ge_u32_e32 vcc, v3, v2
	v_add_u32_e32 v3, 1, v5
	s_nop 0
	v_cndmask_b32_e32 v1, v1, v4, vcc
	v_mul_lo_u32 v4, v2, v1
	v_add_u32_e32 v2, v4, v2
	v_cmp_ne_u32_e32 vcc, v3, v2
	s_and_saveexec_b64 s[0:1], vcc
	s_xor_b64 s[14:15], exec, s[0:1]
	s_cbranch_execz .LBB0_1917
	s_waitcnt lgkmcnt(0)
	v_mov_b32_e32 v0, 0x20044
	ds_read_b32 v2, v0
	v_mov_b32_e32 v0, 0x7000
	global_load_dword v0, v0, s[8:9] offset:1024 sc1
	s_add_u32 s20, s8, 0x7400
	s_addc_u32 s21, s9, 0
	s_waitcnt lgkmcnt(0)
	v_mad_u32_u24 v1, v1, v2, v2
	s_waitcnt vmcnt(0)
	v_cmp_lt_u32_e32 vcc, v0, v1
	s_and_saveexec_b64 s[16:17], vcc
	s_cbranch_execz .LBB0_1916
	s_add_u32 s18, s8, 0x4200
	s_addc_u32 s19, s9, 0
	s_mov_b32 s0, 1
	s_mov_b64 s[22:23], 0
	v_mov_b32_e32 v0, 0
	s_branch .LBB0_1907

; __device__ __forceinline__ unsigned xb_ld(unsigned* p)              { return __hip_atomic_load(p, __ATOMIC_RELAXED, __HIP_MEMORY_SCOPE_AGENT); }
; #define XB_SPIN(cond, bar) do { unsigned _sp = 0; while (cond) { __builtin_amdgcn_s_sleep(1); \
;     if ((++_sp & 255u) == 0u) { if (xb_ld(&(bar)[XB_TMO])) break; if (_sp > XB_SPIN_CAP) { atomicAdd(&(bar)[XB_TMO], 1u); break; } } } } while (0)
; __device__ __forceinline__ void xcd_barrier(const XcdBarrier& b) {
;     ...
;             XB_SPIN(xb_ld(&bar[XB_XGEN(b.x)]) == gen, bar);
.LBB0_1911:
	global_load_dword v2, v0, s[20:21] sc1
	s_add_i32 s0, s0, 1
	s_mov_b64 s[34:35], -1
	s_waitcnt vmcnt(0)
	v_cmp_ge_u32_e32 vcc, v2, v1
	s_orn2_b64 s[26:27], vcc, exec
	s_branch .LBB0_1906

; __device__ __forceinline__ unsigned xb_ld(unsigned* p)              { return __hip_atomic_load(p, __ATOMIC_RELAXED, __HIP_MEMORY_SCOPE_AGENT); }
; __device__ __forceinline__ unsigned xb_add(unsigned* p, unsigned v) { return __hip_atomic_fetch_add(p, v, __ATOMIC_RELAXED, __HIP_MEMORY_SCOPE_AGENT); }
; #define XB_SPIN(cond, bar) do { unsigned _sp = 0; while (cond) { __builtin_amdgcn_s_sleep(1); \
;     if ((++_sp & 255u) == 0u) { if (xb_ld(&(bar)[XB_TMO])) break; if (_sp > XB_SPIN_CAP) { atomicAdd(&(bar)[XB_TMO], 1u); break; } } } } while (0)
; __device__ __forceinline__ void xcd_barrier(const XcdBarrier& b) {
;     ...
;         if (old + 1u == (gen + 1u) * nloc) {
;             __builtin_amdgcn_fence(__ATOMIC_RELEASE, "agent");
;             asm volatile("s_waitcnt vmcnt(0)" ::: "memory");
;             const unsigned og = xb_add(&bar[XB_TOP], 1u);
;             const unsigned tg = og / nx;
;             if (og + 1u == (tg + 1u) * nx) xb_add(&bar[XB_TOPGEN], 1u);
;             else XB_SPIN(xb_ld(&bar[XB_TOPGEN]) == tg, bar);
.LBB0_1920:
	s_or_b64 exec, exec, s[16:17]
	v_cvt_f32_u32_e32 v3, v0
	s_waitcnt vmcnt(0)
	v_readfirstlane_b32 s0, v2
	s_add_u32 s16, s8, 0x7500
	s_addc_u32 s17, s9, 0
	v_rcp_iflag_f32_e32 v3, v3
	v_add_u32_e32 v1, s0, v1
	v_add_u32_e32 v4, 1, v1
	s_mov_b64 s[18:19], -1
	v_mul_f32_e32 v2, 0x4f7ffffe, v3
	v_cvt_u32_f32_e32 v2, v2
	v_sub_u32_e32 v3, 0, v0
	v_mul_lo_u32 v3, v3, v2
	v_mul_hi_u32 v3, v2, v3
	v_add_u32_e32 v2, v2, v3
	v_mul_hi_u32 v2, v1, v2
	v_mul_lo_u32 v3, v2, v0
	v_sub_u32_e32 v1, v1, v3
	v_add_u32_e32 v5, 1, v2
	v_cmp_ge_u32_e32 vcc, v1, v0
	v_sub_u32_e32 v3, v1, v0
	s_nop 0
	v_cndmask_b32_e32 v2, v2, v5, vcc
	v_cndmask_b32_e32 v1, v1, v3, vcc
	v_add_u32_e32 v3, 1, v2
	v_cmp_ge_u32_e32 vcc, v1, v0
	s_nop 1
	v_cndmask_b32_e32 v2, v2, v3, vcc
	v_mul_lo_u32 v1, v0, v2
	v_add_u32_e32 v0, v1, v0
	v_cmp_ne_u32_e32 vcc, v4, v0
	v_mov_b32_e32 v2, v0
	v_mov_b64_e32 v[0:1], s[16:17]
	s_and_saveexec_b64 s[14:15], vcc
	s_cbranch_execz .LBB0_1932
	v_mov_b32_e32 v0, 0
	global_load_dword v1, v0, s[16:17] offset:-256 sc1
	s_mov_b64 s[22:23], 0
	s_waitcnt vmcnt(0)
	v_cmp_lt_u32_e32 vcc, v1, v2
	s_and_saveexec_b64 s[20:21], vcc
	s_cbranch_execz .LBB0_1931
	s_add_u32 s18, s8, 0x4200
	s_addc_u32 s19, s9, 0
	s_mov_b32 s0, 1
	s_mov_b64 s[8:9], 0
	s_branch .LBB0_1924

; __device__ __forceinline__ unsigned xb_ld(unsigned* p)              { return __hip_atomic_load(p, __ATOMIC_RELAXED, __HIP_MEMORY_SCOPE_AGENT); }
; #define XB_SPIN(cond, bar) do { unsigned _sp = 0; while (cond) { __builtin_amdgcn_s_sleep(1); \
;     if ((++_sp & 255u) == 0u) { if (xb_ld(&(bar)[XB_TMO])) break; if (_sp > XB_SPIN_CAP) { atomicAdd(&(bar)[XB_TMO], 1u); break; } } } } while (0)
; __device__ __forceinline__ void xcd_barrier(const XcdBarrier& b) {
;     ...
;             else XB_SPIN(xb_ld(&bar[XB_TOPGEN]) == tg, bar);
.LBB0_1928:
	global_load_dword v1, v0, s[16:17] offset:-256 sc1
	s_add_i32 s0, s0, 1
	s_mov_b64 s[24:25], -1
	s_waitcnt vmcnt(0)
	v_cmp_ge_u32_e32 vcc, v1, v2
	s_orn2_b64 s[34:35], vcc, exec
	s_branch .LBB0_1923

; __device__ __forceinline__ unsigned xb_ld(unsigned* p)              { return __hip_atomic_load(p, __ATOMIC_RELAXED, __HIP_MEMORY_SCOPE_AGENT); }
; __device__ __forceinline__ unsigned xb_add(unsigned* p, unsigned v) { return __hip_atomic_fetch_add(p, v, __ATOMIC_RELAXED, __HIP_MEMORY_SCOPE_AGENT); }
; #define XB_SPIN(cond, bar) do { unsigned _sp = 0; while (cond) { __builtin_amdgcn_s_sleep(1); \
;     if ((++_sp & 255u) == 0u) { if (xb_ld(&(bar)[XB_TMO])) break; if (_sp > XB_SPIN_CAP) { atomicAdd(&(bar)[XB_TMO], 1u); break; } } } } while (0)
; __device__ __forceinline__ void xcd_barrier(const XcdBarrier& b) {
;     ...
;         const unsigned old = xb_add(&bar[XB_XSUB(b.x)], 1u);
;         const unsigned gen = old / nloc;
;         if (old + 1u == (gen + 1u) * nloc) {
;             __builtin_amdgcn_fence(__ATOMIC_RELEASE, "agent");
;             asm volatile("s_waitcnt vmcnt(0)" ::: "memory");
;             const unsigned og = xb_add(&bar[XB_TOP], 1u);
;             const unsigned tg = og / nx;
;             if (og + 1u == (tg + 1u) * nx) xb_add(&bar[XB_TOPGEN], 1u);
;             else XB_SPIN(xb_ld(&bar[XB_TOPGEN]) == tg, bar);
;             __builtin_amdgcn_fence(__ATOMIC_ACQUIRE, "agent");
;             xb_add(&bar[XB_XGEN(b.x)], 1u);
;             asm volatile("s_waitcnt vmcnt(0)" ::: "memory");
;         } else {
;             XB_SPIN(xb_ld(&bar[XB_XGEN(b.x)]) == gen, bar);
.LBB0_2065:
	s_or_b64 exec, exec, s[14:15]
	v_cvt_f32_u32_e32 v4, v2
	s_waitcnt vmcnt(0)
	v_readfirstlane_b32 s0, v3
	v_sub_u32_e32 v3, 0, v2
	v_rcp_iflag_f32_e32 v4, v4
	v_add_u32_e32 v5, s0, v1
	v_mul_f32_e32 v4, 0x4f7ffffe, v4
	v_cvt_u32_f32_e32 v4, v4
	v_mul_lo_u32 v1, v3, v4
	v_mul_hi_u32 v1, v4, v1
	v_add_u32_e32 v1, v4, v1
	v_mul_hi_u32 v1, v5, v1
	v_mul_lo_u32 v3, v1, v2
	v_sub_u32_e32 v3, v5, v3
	v_add_u32_e32 v4, 1, v1
	v_cmp_ge_u32_e32 vcc, v3, v2
	s_nop 1
	v_cndmask_b32_e32 v1, v1, v4, vcc
	v_sub_u32_e32 v4, v3, v2
	v_cndmask_b32_e32 v3, v3, v4, vcc
	v_add_u32_e32 v4, 1, v1
	v_cmp_ge_u32_e32 vcc, v3, v2
	v_add_u32_e32 v3, 1, v5
	s_nop 0
	v_cndmask_b32_e32 v1, v1, v4, vcc
	v_mul_lo_u32 v4, v2, v1
	v_add_u32_e32 v2, v4, v2
	v_cmp_ne_u32_e32 vcc, v3, v2
	s_and_saveexec_b64 s[0:1], vcc
	s_xor_b64 s[12:13], exec, s[0:1]
	s_cbranch_execz .LBB0_2079
	s_waitcnt lgkmcnt(0)
	v_mov_b32_e32 v0, 0x20044
	ds_read_b32 v2, v0
	v_mov_b32_e32 v0, 0x7000
	global_load_dword v0, v0, s[8:9] offset:1024 sc1
	s_add_u32 s18, s8, 0x7400
	s_addc_u32 s19, s9, 0
	s_waitcnt lgkmcnt(0)
	v_mad_u32_u24 v1, v1, v2, v2
	s_waitcnt vmcnt(0)
	v_cmp_lt_u32_e32 vcc, v0, v1
	s_and_saveexec_b64 s[14:15], vcc
	s_cbranch_execz .LBB0_2078
	s_add_u32 s16, s8, 0x4200
	s_addc_u32 s17, s9, 0
	s_mov_b32 s0, 1
	s_mov_b64 s[20:21], 0
	v_mov_b32_e32 v0, 0
	s_branch .LBB0_2069

; __device__ __forceinline__ unsigned xb_ld(unsigned* p)              { return __hip_atomic_load(p, __ATOMIC_RELAXED, __HIP_MEMORY_SCOPE_AGENT); }
; #define XB_SPIN(cond, bar) do { unsigned _sp = 0; while (cond) { __builtin_amdgcn_s_sleep(1); \
;     if ((++_sp & 255u) == 0u) { if (xb_ld(&(bar)[XB_TMO])) break; if (_sp > XB_SPIN_CAP) { atomicAdd(&(bar)[XB_TMO], 1u); break; } } } } while (0)
; __device__ __forceinline__ void xcd_barrier(const XcdBarrier& b) {
;     ...
;             XB_SPIN(xb_ld(&bar[XB_XGEN(b.x)]) == gen, bar);
.LBB0_2073:
	global_load_dword v2, v0, s[18:19] sc1
	s_add_i32 s0, s0, 1
	s_mov_b64 s[26:27], -1
	s_waitcnt vmcnt(0)
	v_cmp_ge_u32_e32 vcc, v2, v1
	s_orn2_b64 s[24:25], vcc, exec
	s_branch .LBB0_2068

; __device__ __forceinline__ unsigned xb_ld(unsigned* p)              { return __hip_atomic_load(p, __ATOMIC_RELAXED, __HIP_MEMORY_SCOPE_AGENT); }
; __device__ __forceinline__ unsigned xb_add(unsigned* p, unsigned v) { return __hip_atomic_fetch_add(p, v, __ATOMIC_RELAXED, __HIP_MEMORY_SCOPE_AGENT); }
; #define XB_SPIN(cond, bar) do { unsigned _sp = 0; while (cond) { __builtin_amdgcn_s_sleep(1); \
;     if ((++_sp & 255u) == 0u) { if (xb_ld(&(bar)[XB_TMO])) break; if (_sp > XB_SPIN_CAP) { atomicAdd(&(bar)[XB_TMO], 1u); break; } } } } while (0)
; __device__ __forceinline__ void xcd_barrier(const XcdBarrier& b) {
;     ...
;         if (old + 1u == (gen + 1u) * nloc) {
;             __builtin_amdgcn_fence(__ATOMIC_RELEASE, "agent");
;             asm volatile("s_waitcnt vmcnt(0)" ::: "memory");
;             const unsigned og = xb_add(&bar[XB_TOP], 1u);
;             const unsigned tg = og / nx;
;             if (og + 1u == (tg + 1u) * nx) xb_add(&bar[XB_TOPGEN], 1u);
;             else XB_SPIN(xb_ld(&bar[XB_TOPGEN]) == tg, bar);
.LBB0_2082:
	s_or_b64 exec, exec, s[14:15]
	v_cvt_f32_u32_e32 v3, v0
	s_waitcnt vmcnt(0)
	v_readfirstlane_b32 s0, v2
	s_add_u32 s14, s8, 0x7500
	s_addc_u32 s15, s9, 0
	v_rcp_iflag_f32_e32 v3, v3
	v_add_u32_e32 v1, s0, v1
	v_add_u32_e32 v4, 1, v1
	s_mov_b64 s[16:17], -1
	v_mul_f32_e32 v2, 0x4f7ffffe, v3
	v_cvt_u32_f32_e32 v2, v2
	v_sub_u32_e32 v3, 0, v0
	v_mul_lo_u32 v3, v3, v2
	v_mul_hi_u32 v3, v2, v3
	v_add_u32_e32 v2, v2, v3
	v_mul_hi_u32 v2, v1, v2
	v_mul_lo_u32 v3, v2, v0
	v_sub_u32_e32 v1, v1, v3
	v_add_u32_e32 v5, 1, v2
	v_cmp_ge_u32_e32 vcc, v1, v0
	v_sub_u32_e32 v3, v1, v0
	s_nop 0
	v_cndmask_b32_e32 v2, v2, v5, vcc
	v_cndmask_b32_e32 v1, v1, v3, vcc
	v_add_u32_e32 v3, 1, v2
	v_cmp_ge_u32_e32 vcc, v1, v0
	s_nop 1
	v_cndmask_b32_e32 v2, v2, v3, vcc
	v_mul_lo_u32 v1, v0, v2
	v_add_u32_e32 v0, v1, v0
	v_cmp_ne_u32_e32 vcc, v4, v0
	v_mov_b32_e32 v2, v0
	v_mov_b64_e32 v[0:1], s[14:15]
	s_and_saveexec_b64 s[12:13], vcc
	s_cbranch_execz .LBB0_2094
	v_mov_b32_e32 v0, 0
	global_load_dword v1, v0, s[14:15] offset:-256 sc1
	s_mov_b64 s[20:21], 0
	s_waitcnt vmcnt(0)
	v_cmp_lt_u32_e32 vcc, v1, v2
	s_and_saveexec_b64 s[18:19], vcc
	s_cbranch_execz .LBB0_2093
	s_add_u32 s16, s8, 0x4200
	s_addc_u32 s17, s9, 0
	s_mov_b32 s0, 1
	s_mov_b64 s[8:9], 0
	s_branch .LBB0_2086

; __device__ __forceinline__ unsigned xb_ld(unsigned* p)              { return __hip_atomic_load(p, __ATOMIC_RELAXED, __HIP_MEMORY_SCOPE_AGENT); }
; #define XB_SPIN(cond, bar) do { unsigned _sp = 0; while (cond) { __builtin_amdgcn_s_sleep(1); \
;     if ((++_sp & 255u) == 0u) { if (xb_ld(&(bar)[XB_TMO])) break; if (_sp > XB_SPIN_CAP) { atomicAdd(&(bar)[XB_TMO], 1u); break; } } } } while (0)
; __device__ __forceinline__ void xcd_barrier(const XcdBarrier& b) {
;     ...
;             else XB_SPIN(xb_ld(&bar[XB_TOPGEN]) == tg, bar);
.LBB0_2090:
	global_load_dword v1, v0, s[14:15] offset:-256 sc1
	s_add_i32 s0, s0, 1
	s_mov_b64 s[22:23], -1
	s_waitcnt vmcnt(0)
	v_cmp_ge_u32_e32 vcc, v1, v2
	s_orn2_b64 s[26:27], vcc, exec
	s_branch .LBB0_2085
